# attention QK/softmax/PV interleave + de-serialised epilogue loads (ssq, residual, gate) in PA2 PA5 PB1 PB2b PB5 attention; hazard-safe placeholders
# speedup vs baseline: 1.0135x; 1.0034x over previous
.LBB0_221:
	v_cvt_pk_bf16_f32 v120, v120, v121
	v_cvt_pk_bf16_f32 v121, v122, v123
	v_cvt_pk_bf16_f32 v122, v116, v117
	s_nop 0
	v_cvt_pk_bf16_f32 v123, v118, v119
	global_store_dwordx4 v[126:127], v[120:123], off offset:256
	s_nop 0
	s_nop 0
	v_fmamk_f32 v116, v241, 0x3a000000, v164
	v_mul_f32_e32 v117, 0x4f800000, v116
	v_cmp_gt_f32_e32 vcc, s93, v116
	s_nop 1
	v_cndmask_b32_e32 v116, v116, v117, vcc
	v_sqrt_f32_e32 v117, v116
	s_nop 0
	v_add_u32_e32 v118, -1, v117
	v_add_u32_e32 v119, 1, v117
	v_fma_f32 v120, -v118, v117, v116
	v_fma_f32 v121, -v119, v117, v116
	v_cmp_ge_f32_e64 s[10:11], 0, v120
	s_nop 1
	v_cndmask_b32_e64 v117, v117, v118, s[10:11]
	v_cmp_lt_f32_e64 s[10:11], 0, v121
	s_nop 1
	v_cndmask_b32_e64 v117, v117, v119, s[10:11]
	v_mul_f32_e32 v118, 0x37800000, v117
	v_cndmask_b32_e32 v117, v117, v118, vcc
	v_cmp_class_f32_e32 vcc, v116, v165
	s_nop 1
	v_cndmask_b32_e32 v116, v117, v116, vcc
	v_div_scale_f32 v117, s[10:11], v116, v116, 1.0
	v_rcp_f32_e32 v118, v117
	v_div_scale_f32 v119, vcc, 1.0, v116, 1.0
	v_fma_f32 v120, -v117, v118, 1.0
	v_fmac_f32_e32 v118, v120, v118
	v_mul_f32_e32 v120, v119, v118
	v_fma_f32 v121, -v117, v120, v119
	v_fmac_f32_e32 v120, v121, v118
	v_fma_f32 v117, -v117, v120, v119
	v_div_fmas_f32 v117, v117, v118, v120
	v_div_fixup_f32 v116, v117, v116, 1.0
	s_and_b64 vcc, exec, s[8:9]
	v_pk_mul_f32 v[114:115], v[114:115], v[116:117] op_sel_hi:[1,0]
	v_pk_mul_f32 v[118:119], v[112:113], v[116:117] op_sel_hi:[1,0]
	v_pk_mul_f32 v[110:111], v[110:111], v[116:117] op_sel_hi:[1,0]
	v_pk_mul_f32 v[112:113], v[108:109], v[116:117] op_sel_hi:[1,0]
	s_cbranch_vccnz .LBB0_223
	v_mul_f32_e32 v117, 0xbfb8aa3b, v114
	v_exp_f32_e32 v117, v117
	v_mul_f32_e32 v108, 0xbfb8aa3b, v118
	v_mul_f32_e32 v109, 0xbfb8aa3b, v119
	v_exp_f32_e32 v108, v108
	v_add_f32_e32 v117, 1.0, v117
	v_rcp_f32_e32 v120, v117
	v_mul_f32_e32 v117, 0xbfb8aa3b, v115
	v_exp_f32_e32 v117, v117
	v_exp_f32_e32 v109, v109
	v_add_f32_e32 v108, 1.0, v108
	v_rcp_f32_e32 v108, v108
	v_add_f32_e32 v117, 1.0, v117
	v_rcp_f32_e32 v121, v117
	v_mul_f32_e32 v117, 0xbfb8aa3b, v110
	v_add_f32_e32 v109, 1.0, v109
	v_exp_f32_e32 v117, v117
	v_rcp_f32_e32 v109, v109
	v_pk_mul_f32 v[114:115], v[114:115], v[120:121]
	v_add_f32_e32 v117, 1.0, v117
	v_pk_mul_f32 v[118:119], v[118:119], v[108:109]
	v_mul_f32_e32 v108, 0xbfb8aa3b, v112
	v_mul_f32_e32 v109, 0xbfb8aa3b, v113
	v_rcp_f32_e32 v120, v117
	v_mul_f32_e32 v117, 0xbfb8aa3b, v111
	v_exp_f32_e32 v108, v108
	v_exp_f32_e32 v109, v109
	v_exp_f32_e32 v117, v117
	v_add_f32_e32 v108, 1.0, v108
	v_add_f32_e32 v109, 1.0, v109
	v_add_f32_e32 v117, 1.0, v117
	v_rcp_f32_e32 v108, v108
	v_rcp_f32_e32 v109, v109
	v_rcp_f32_e32 v121, v117
	v_pk_mul_f32 v[112:113], v[112:113], v[108:109]
	v_pk_mul_f32 v[110:111], v[110:111], v[120:121]

.LBB0_225:
	v_cvt_pk_bf16_f32 v104, v104, v105
	v_cvt_pk_bf16_f32 v105, v106, v107
	v_cvt_pk_bf16_f32 v106, v100, v101
	s_nop 0
	v_cvt_pk_bf16_f32 v107, v102, v103
	global_store_dwordx4 v[108:109], v[104:107], off offset:256
	s_nop 0
	s_nop 0
	v_fmamk_f32 v100, v242, 0x3a000000, v164
	v_mul_f32_e32 v101, 0x4f800000, v100
	v_cmp_gt_f32_e32 vcc, s93, v100
	s_nop 1
	v_cndmask_b32_e32 v100, v100, v101, vcc
	v_sqrt_f32_e32 v101, v100
	s_nop 0
	v_add_u32_e32 v102, -1, v101
	v_add_u32_e32 v103, 1, v101
	v_fma_f32 v104, -v102, v101, v100
	v_fma_f32 v105, -v103, v101, v100
	v_cmp_ge_f32_e64 s[10:11], 0, v104
	s_nop 1
	v_cndmask_b32_e64 v101, v101, v102, s[10:11]
	v_cmp_lt_f32_e64 s[10:11], 0, v105
	s_nop 1
	v_cndmask_b32_e64 v101, v101, v103, s[10:11]
	v_mul_f32_e32 v102, 0x37800000, v101
	v_cndmask_b32_e32 v101, v101, v102, vcc
	v_cmp_class_f32_e32 vcc, v100, v165
	s_nop 1
	v_cndmask_b32_e32 v100, v101, v100, vcc
	v_div_scale_f32 v101, s[10:11], v100, v100, 1.0
	v_rcp_f32_e32 v102, v101
	v_div_scale_f32 v103, vcc, 1.0, v100, 1.0
	v_fma_f32 v104, -v101, v102, 1.0
	v_fmac_f32_e32 v102, v104, v102
	v_mul_f32_e32 v104, v103, v102
	v_fma_f32 v105, -v101, v104, v103
	v_fmac_f32_e32 v104, v105, v102
	v_fma_f32 v101, -v101, v104, v103
	v_div_fmas_f32 v101, v101, v102, v104
	v_div_fixup_f32 v100, v101, v100, 1.0
	s_and_b64 vcc, exec, s[8:9]
	v_pk_mul_f32 v[98:99], v[98:99], v[100:101] op_sel_hi:[1,0]
	v_pk_mul_f32 v[102:103], v[96:97], v[100:101] op_sel_hi:[1,0]
	v_pk_mul_f32 v[94:95], v[94:95], v[100:101] op_sel_hi:[1,0]
	v_pk_mul_f32 v[96:97], v[92:93], v[100:101] op_sel_hi:[1,0]
	s_cbranch_vccnz .LBB0_227
	v_mul_f32_e32 v101, 0xbfb8aa3b, v98
	v_exp_f32_e32 v101, v101
	v_mul_f32_e32 v92, 0xbfb8aa3b, v102
	v_mul_f32_e32 v93, 0xbfb8aa3b, v103
	v_exp_f32_e32 v92, v92
	v_add_f32_e32 v101, 1.0, v101
	v_rcp_f32_e32 v104, v101
	v_mul_f32_e32 v101, 0xbfb8aa3b, v99
	v_exp_f32_e32 v101, v101
	v_exp_f32_e32 v93, v93
	v_add_f32_e32 v92, 1.0, v92
	v_rcp_f32_e32 v92, v92
	v_add_f32_e32 v101, 1.0, v101
	v_rcp_f32_e32 v105, v101
	v_mul_f32_e32 v101, 0xbfb8aa3b, v94
	v_add_f32_e32 v93, 1.0, v93
	v_exp_f32_e32 v101, v101
	v_rcp_f32_e32 v93, v93
	v_pk_mul_f32 v[98:99], v[98:99], v[104:105]
	v_add_f32_e32 v101, 1.0, v101
	v_pk_mul_f32 v[102:103], v[102:103], v[92:93]
	v_mul_f32_e32 v92, 0xbfb8aa3b, v96
	v_mul_f32_e32 v93, 0xbfb8aa3b, v97
	v_rcp_f32_e32 v104, v101
	v_mul_f32_e32 v101, 0xbfb8aa3b, v95
	v_exp_f32_e32 v92, v92
	v_exp_f32_e32 v93, v93
	v_exp_f32_e32 v101, v101
	v_add_f32_e32 v92, 1.0, v92
	v_add_f32_e32 v93, 1.0, v93
	v_add_f32_e32 v101, 1.0, v101
	v_rcp_f32_e32 v92, v92
	v_rcp_f32_e32 v93, v93
	v_rcp_f32_e32 v105, v101
	v_pk_mul_f32 v[96:97], v[96:97], v[92:93]
	v_pk_mul_f32 v[94:95], v[94:95], v[104:105]

.LBB0_229:
	v_cvt_pk_bf16_f32 v88, v88, v89
	v_cvt_pk_bf16_f32 v89, v90, v91
	v_cvt_pk_bf16_f32 v90, v84, v85
	s_nop 0
	v_cvt_pk_bf16_f32 v91, v86, v87
	global_store_dwordx4 v[92:93], v[88:91], off offset:256
	s_nop 0
	s_nop 0
	v_fmamk_f32 v84, v243, 0x3a000000, v164
	v_mul_f32_e32 v85, 0x4f800000, v84
	v_cmp_gt_f32_e32 vcc, s93, v84
	s_nop 1
	v_cndmask_b32_e32 v84, v84, v85, vcc
	v_sqrt_f32_e32 v85, v84
	s_nop 0
	v_add_u32_e32 v86, -1, v85
	v_add_u32_e32 v87, 1, v85
	v_fma_f32 v88, -v86, v85, v84
	v_fma_f32 v89, -v87, v85, v84
	v_cmp_ge_f32_e64 s[10:11], 0, v88
	s_nop 1
	v_cndmask_b32_e64 v85, v85, v86, s[10:11]
	v_cmp_lt_f32_e64 s[10:11], 0, v89
	s_nop 1
	v_cndmask_b32_e64 v85, v85, v87, s[10:11]
	v_mul_f32_e32 v86, 0x37800000, v85
	v_cndmask_b32_e32 v85, v85, v86, vcc
	v_cmp_class_f32_e32 vcc, v84, v165
	s_nop 1
	v_cndmask_b32_e32 v84, v85, v84, vcc
	v_div_scale_f32 v85, s[10:11], v84, v84, 1.0
	v_rcp_f32_e32 v86, v85
	v_div_scale_f32 v87, vcc, 1.0, v84, 1.0
	v_fma_f32 v88, -v85, v86, 1.0
	v_fmac_f32_e32 v86, v88, v86
	v_mul_f32_e32 v88, v87, v86
	v_fma_f32 v89, -v85, v88, v87
	v_fmac_f32_e32 v88, v89, v86
	v_fma_f32 v85, -v85, v88, v87
	v_div_fmas_f32 v85, v85, v86, v88
	v_div_fixup_f32 v84, v85, v84, 1.0
	s_and_b64 vcc, exec, s[8:9]
	v_pk_mul_f32 v[82:83], v[82:83], v[84:85] op_sel_hi:[1,0]
	v_pk_mul_f32 v[86:87], v[80:81], v[84:85] op_sel_hi:[1,0]
	v_pk_mul_f32 v[78:79], v[78:79], v[84:85] op_sel_hi:[1,0]
	v_pk_mul_f32 v[80:81], v[76:77], v[84:85] op_sel_hi:[1,0]
	s_cbranch_vccnz .LBB0_231
	v_mul_f32_e32 v85, 0xbfb8aa3b, v82
	v_exp_f32_e32 v85, v85
	v_mul_f32_e32 v76, 0xbfb8aa3b, v86
	v_mul_f32_e32 v77, 0xbfb8aa3b, v87
	v_exp_f32_e32 v76, v76
	v_add_f32_e32 v85, 1.0, v85
	v_rcp_f32_e32 v88, v85
	v_mul_f32_e32 v85, 0xbfb8aa3b, v83
	v_exp_f32_e32 v85, v85
	v_exp_f32_e32 v77, v77
	v_add_f32_e32 v76, 1.0, v76
	v_rcp_f32_e32 v76, v76
	v_add_f32_e32 v85, 1.0, v85
	v_rcp_f32_e32 v89, v85
	v_mul_f32_e32 v85, 0xbfb8aa3b, v78
	v_add_f32_e32 v77, 1.0, v77
	v_exp_f32_e32 v85, v85
	v_rcp_f32_e32 v77, v77
	v_pk_mul_f32 v[82:83], v[82:83], v[88:89]
	v_add_f32_e32 v85, 1.0, v85
	v_pk_mul_f32 v[86:87], v[86:87], v[76:77]
	v_mul_f32_e32 v76, 0xbfb8aa3b, v80
	v_mul_f32_e32 v77, 0xbfb8aa3b, v81
	v_rcp_f32_e32 v88, v85
	v_mul_f32_e32 v85, 0xbfb8aa3b, v79
	v_exp_f32_e32 v76, v76
	v_exp_f32_e32 v77, v77
	v_exp_f32_e32 v85, v85
	v_add_f32_e32 v76, 1.0, v76
	v_add_f32_e32 v77, 1.0, v77
	v_add_f32_e32 v85, 1.0, v85
	v_rcp_f32_e32 v76, v76
	v_rcp_f32_e32 v77, v77
	v_rcp_f32_e32 v89, v85
	v_pk_mul_f32 v[80:81], v[80:81], v[76:77]
	v_pk_mul_f32 v[78:79], v[78:79], v[88:89]

.LBB0_233:
	v_cvt_pk_bf16_f32 v72, v72, v73
	v_cvt_pk_bf16_f32 v73, v74, v75
	v_cvt_pk_bf16_f32 v74, v68, v69
	s_nop 0
	v_cvt_pk_bf16_f32 v75, v70, v71
	global_store_dwordx4 v[76:77], v[72:75], off offset:256
	s_nop 0
	s_nop 0
	v_fmamk_f32 v68, v244, 0x3a000000, v164
	v_mul_f32_e32 v69, 0x4f800000, v68
	v_cmp_gt_f32_e32 vcc, s93, v68
	s_nop 1
	v_cndmask_b32_e32 v68, v68, v69, vcc
	v_sqrt_f32_e32 v69, v68
	s_nop 0
	v_add_u32_e32 v70, -1, v69
	v_add_u32_e32 v71, 1, v69
	v_fma_f32 v72, -v70, v69, v68
	v_fma_f32 v73, -v71, v69, v68
	v_cmp_ge_f32_e64 s[10:11], 0, v72
	s_nop 1
	v_cndmask_b32_e64 v69, v69, v70, s[10:11]
	v_cmp_lt_f32_e64 s[10:11], 0, v73
	s_nop 1
	v_cndmask_b32_e64 v69, v69, v71, s[10:11]
	v_mul_f32_e32 v70, 0x37800000, v69
	v_cndmask_b32_e32 v69, v69, v70, vcc
	v_cmp_class_f32_e32 vcc, v68, v165
	s_nop 1
	v_cndmask_b32_e32 v68, v69, v68, vcc
	v_div_scale_f32 v69, s[10:11], v68, v68, 1.0
	v_rcp_f32_e32 v70, v69
	v_div_scale_f32 v71, vcc, 1.0, v68, 1.0
	v_fma_f32 v72, -v69, v70, 1.0
	v_fmac_f32_e32 v70, v72, v70
	v_mul_f32_e32 v72, v71, v70
	v_fma_f32 v73, -v69, v72, v71
	v_fmac_f32_e32 v72, v73, v70
	v_fma_f32 v69, -v69, v72, v71
	v_div_fmas_f32 v69, v69, v70, v72
	v_div_fixup_f32 v68, v69, v68, 1.0
	s_and_b64 vcc, exec, s[8:9]
	v_pk_mul_f32 v[66:67], v[66:67], v[68:69] op_sel_hi:[1,0]
	v_pk_mul_f32 v[70:71], v[64:65], v[68:69] op_sel_hi:[1,0]
	v_pk_mul_f32 v[62:63], v[62:63], v[68:69] op_sel_hi:[1,0]
	v_pk_mul_f32 v[64:65], v[60:61], v[68:69] op_sel_hi:[1,0]
	s_cbranch_vccnz .LBB0_235
	v_mul_f32_e32 v69, 0xbfb8aa3b, v66
	v_exp_f32_e32 v69, v69
	v_mul_f32_e32 v60, 0xbfb8aa3b, v70
	v_mul_f32_e32 v61, 0xbfb8aa3b, v71
	v_exp_f32_e32 v60, v60
	v_add_f32_e32 v69, 1.0, v69
	v_rcp_f32_e32 v72, v69
	v_mul_f32_e32 v69, 0xbfb8aa3b, v67
	v_exp_f32_e32 v69, v69
	v_exp_f32_e32 v61, v61
	v_add_f32_e32 v60, 1.0, v60
	v_rcp_f32_e32 v60, v60
	v_add_f32_e32 v69, 1.0, v69
	v_rcp_f32_e32 v73, v69
	v_mul_f32_e32 v69, 0xbfb8aa3b, v62
	v_add_f32_e32 v61, 1.0, v61
	v_exp_f32_e32 v69, v69
	v_rcp_f32_e32 v61, v61
	v_pk_mul_f32 v[66:67], v[66:67], v[72:73]
	v_add_f32_e32 v69, 1.0, v69
	v_pk_mul_f32 v[70:71], v[70:71], v[60:61]
	v_mul_f32_e32 v60, 0xbfb8aa3b, v64
	v_mul_f32_e32 v61, 0xbfb8aa3b, v65
	v_rcp_f32_e32 v72, v69
	v_mul_f32_e32 v69, 0xbfb8aa3b, v63
	v_exp_f32_e32 v60, v60
	v_exp_f32_e32 v61, v61
	v_exp_f32_e32 v69, v69
	v_add_f32_e32 v60, 1.0, v60
	v_add_f32_e32 v61, 1.0, v61
	v_add_f32_e32 v69, 1.0, v69
	v_rcp_f32_e32 v60, v60
	v_rcp_f32_e32 v61, v61
	v_rcp_f32_e32 v73, v69
	v_pk_mul_f32 v[64:65], v[64:65], v[60:61]
	v_pk_mul_f32 v[62:63], v[62:63], v[72:73]

.LBB0_237:
	v_cvt_pk_bf16_f32 v56, v56, v57
	v_cvt_pk_bf16_f32 v57, v58, v59
	v_cvt_pk_bf16_f32 v58, v52, v53
	s_nop 0
	v_cvt_pk_bf16_f32 v59, v54, v55
	global_store_dwordx4 v[60:61], v[56:59], off offset:256
	s_nop 0
	s_nop 0
	v_fmamk_f32 v52, v245, 0x3a000000, v164
	v_mul_f32_e32 v53, 0x4f800000, v52
	v_cmp_gt_f32_e32 vcc, s93, v52
	s_nop 1
	v_cndmask_b32_e32 v52, v52, v53, vcc
	v_sqrt_f32_e32 v53, v52
	s_nop 0
	v_add_u32_e32 v54, -1, v53
	v_add_u32_e32 v55, 1, v53
	v_fma_f32 v56, -v54, v53, v52
	v_fma_f32 v57, -v55, v53, v52
	v_cmp_ge_f32_e64 s[10:11], 0, v56
	s_nop 1
	v_cndmask_b32_e64 v53, v53, v54, s[10:11]
	v_cmp_lt_f32_e64 s[10:11], 0, v57
	s_nop 1
	v_cndmask_b32_e64 v53, v53, v55, s[10:11]
	v_mul_f32_e32 v54, 0x37800000, v53
	v_cndmask_b32_e32 v53, v53, v54, vcc
	v_cmp_class_f32_e32 vcc, v52, v165
	s_nop 1
	v_cndmask_b32_e32 v52, v53, v52, vcc
	v_div_scale_f32 v53, s[10:11], v52, v52, 1.0
	v_rcp_f32_e32 v54, v53
	v_div_scale_f32 v55, vcc, 1.0, v52, 1.0
	v_fma_f32 v56, -v53, v54, 1.0
	v_fmac_f32_e32 v54, v56, v54
	v_mul_f32_e32 v56, v55, v54
	v_fma_f32 v57, -v53, v56, v55
	v_fmac_f32_e32 v56, v57, v54
	v_fma_f32 v53, -v53, v56, v55
	v_div_fmas_f32 v53, v53, v54, v56
	v_div_fixup_f32 v52, v53, v52, 1.0
	s_and_b64 vcc, exec, s[8:9]
	v_pk_mul_f32 v[50:51], v[50:51], v[52:53] op_sel_hi:[1,0]
	v_pk_mul_f32 v[54:55], v[48:49], v[52:53] op_sel_hi:[1,0]
	v_pk_mul_f32 v[46:47], v[46:47], v[52:53] op_sel_hi:[1,0]
	v_pk_mul_f32 v[48:49], v[44:45], v[52:53] op_sel_hi:[1,0]
	s_cbranch_vccnz .LBB0_239
	v_mul_f32_e32 v53, 0xbfb8aa3b, v50
	v_exp_f32_e32 v53, v53
	v_mul_f32_e32 v44, 0xbfb8aa3b, v54
	v_mul_f32_e32 v45, 0xbfb8aa3b, v55
	v_exp_f32_e32 v44, v44
	v_add_f32_e32 v53, 1.0, v53
	v_rcp_f32_e32 v56, v53
	v_mul_f32_e32 v53, 0xbfb8aa3b, v51
	v_exp_f32_e32 v53, v53
	v_exp_f32_e32 v45, v45
	v_add_f32_e32 v44, 1.0, v44
	v_rcp_f32_e32 v44, v44
	v_add_f32_e32 v53, 1.0, v53
	v_rcp_f32_e32 v57, v53
	v_mul_f32_e32 v53, 0xbfb8aa3b, v46
	v_add_f32_e32 v45, 1.0, v45
	v_exp_f32_e32 v53, v53
	v_rcp_f32_e32 v45, v45
	v_pk_mul_f32 v[50:51], v[50:51], v[56:57]
	v_add_f32_e32 v53, 1.0, v53
	v_pk_mul_f32 v[54:55], v[54:55], v[44:45]
	v_mul_f32_e32 v44, 0xbfb8aa3b, v48
	v_mul_f32_e32 v45, 0xbfb8aa3b, v49
	v_rcp_f32_e32 v56, v53
	v_mul_f32_e32 v53, 0xbfb8aa3b, v47
	v_exp_f32_e32 v44, v44
	v_exp_f32_e32 v45, v45
	v_exp_f32_e32 v53, v53
	v_add_f32_e32 v44, 1.0, v44
	v_add_f32_e32 v45, 1.0, v45
	v_add_f32_e32 v53, 1.0, v53
	v_rcp_f32_e32 v44, v44
	v_rcp_f32_e32 v45, v45
	v_rcp_f32_e32 v57, v53
	v_pk_mul_f32 v[48:49], v[48:49], v[44:45]
	v_pk_mul_f32 v[46:47], v[46:47], v[56:57]

.LBB0_241:
	v_cvt_pk_bf16_f32 v40, v40, v41
	v_cvt_pk_bf16_f32 v41, v42, v43
	v_cvt_pk_bf16_f32 v42, v36, v37
	s_nop 0
	v_cvt_pk_bf16_f32 v43, v38, v39
	global_store_dwordx4 v[44:45], v[40:43], off offset:256
	s_nop 0
	s_nop 0
	v_fmamk_f32 v36, v246, 0x3a000000, v164
	v_mul_f32_e32 v37, 0x4f800000, v36
	v_cmp_gt_f32_e32 vcc, s93, v36
	s_nop 1
	v_cndmask_b32_e32 v36, v36, v37, vcc
	v_sqrt_f32_e32 v37, v36
	s_nop 0
	v_add_u32_e32 v38, -1, v37
	v_add_u32_e32 v39, 1, v37
	v_fma_f32 v40, -v38, v37, v36
	v_fma_f32 v41, -v39, v37, v36
	v_cmp_ge_f32_e64 s[10:11], 0, v40
	s_nop 1
	v_cndmask_b32_e64 v37, v37, v38, s[10:11]
	v_cmp_lt_f32_e64 s[10:11], 0, v41
	s_nop 1
	v_cndmask_b32_e64 v37, v37, v39, s[10:11]
	v_mul_f32_e32 v38, 0x37800000, v37
	v_cndmask_b32_e32 v37, v37, v38, vcc
	v_cmp_class_f32_e32 vcc, v36, v165
	s_nop 1
	v_cndmask_b32_e32 v36, v37, v36, vcc
	v_div_scale_f32 v37, s[10:11], v36, v36, 1.0
	v_rcp_f32_e32 v38, v37
	v_div_scale_f32 v39, vcc, 1.0, v36, 1.0
	v_fma_f32 v40, -v37, v38, 1.0
	v_fmac_f32_e32 v38, v40, v38
	v_mul_f32_e32 v40, v39, v38
	v_fma_f32 v41, -v37, v40, v39
	v_fmac_f32_e32 v40, v41, v38
	v_fma_f32 v37, -v37, v40, v39
	v_div_fmas_f32 v37, v37, v38, v40
	v_div_fixup_f32 v36, v37, v36, 1.0
	s_and_b64 vcc, exec, s[8:9]
	v_pk_mul_f32 v[34:35], v[34:35], v[36:37] op_sel_hi:[1,0]
	v_pk_mul_f32 v[38:39], v[32:33], v[36:37] op_sel_hi:[1,0]
	v_pk_mul_f32 v[30:31], v[30:31], v[36:37] op_sel_hi:[1,0]
	v_pk_mul_f32 v[32:33], v[28:29], v[36:37] op_sel_hi:[1,0]
	s_cbranch_vccnz .LBB0_243
	v_mul_f32_e32 v37, 0xbfb8aa3b, v34
	v_exp_f32_e32 v37, v37
	v_mul_f32_e32 v28, 0xbfb8aa3b, v38
	v_mul_f32_e32 v29, 0xbfb8aa3b, v39
	v_exp_f32_e32 v28, v28
	v_add_f32_e32 v37, 1.0, v37
	v_rcp_f32_e32 v40, v37
	v_mul_f32_e32 v37, 0xbfb8aa3b, v35
	v_exp_f32_e32 v37, v37
	v_exp_f32_e32 v29, v29
	v_add_f32_e32 v28, 1.0, v28
	v_rcp_f32_e32 v28, v28
	v_add_f32_e32 v37, 1.0, v37
	v_rcp_f32_e32 v41, v37
	v_mul_f32_e32 v37, 0xbfb8aa3b, v30
	v_add_f32_e32 v29, 1.0, v29
	v_exp_f32_e32 v37, v37
	v_rcp_f32_e32 v29, v29
	v_pk_mul_f32 v[34:35], v[34:35], v[40:41]
	v_add_f32_e32 v37, 1.0, v37
	v_pk_mul_f32 v[38:39], v[38:39], v[28:29]
	v_mul_f32_e32 v28, 0xbfb8aa3b, v32
	v_mul_f32_e32 v29, 0xbfb8aa3b, v33
	v_rcp_f32_e32 v40, v37
	v_mul_f32_e32 v37, 0xbfb8aa3b, v31
	v_exp_f32_e32 v28, v28
	v_exp_f32_e32 v29, v29
	v_exp_f32_e32 v37, v37
	v_add_f32_e32 v28, 1.0, v28
	v_add_f32_e32 v29, 1.0, v29
	v_add_f32_e32 v37, 1.0, v37
	v_rcp_f32_e32 v28, v28
	v_rcp_f32_e32 v29, v29
	v_rcp_f32_e32 v41, v37
	v_pk_mul_f32 v[32:33], v[32:33], v[28:29]
	v_pk_mul_f32 v[30:31], v[30:31], v[40:41]

.LBB0_245:
	v_cvt_pk_bf16_f32 v24, v24, v25
	v_cvt_pk_bf16_f32 v25, v26, v27
	v_cvt_pk_bf16_f32 v26, v20, v21
	s_nop 0
	v_cvt_pk_bf16_f32 v27, v22, v23
	global_store_dwordx4 v[28:29], v[24:27], off offset:256
	s_nop 0
	s_nop 0
	v_fmamk_f32 v20, v247, 0x3a000000, v164
	v_mul_f32_e32 v21, 0x4f800000, v20
	v_cmp_gt_f32_e32 vcc, s93, v20
	s_nop 1
	v_cndmask_b32_e32 v20, v20, v21, vcc
	v_sqrt_f32_e32 v21, v20
	s_nop 0
	v_add_u32_e32 v22, -1, v21
	v_add_u32_e32 v23, 1, v21
	v_fma_f32 v24, -v22, v21, v20
	v_fma_f32 v25, -v23, v21, v20
	v_cmp_ge_f32_e64 s[10:11], 0, v24
	s_nop 1
	v_cndmask_b32_e64 v21, v21, v22, s[10:11]
	v_cmp_lt_f32_e64 s[10:11], 0, v25
	s_nop 1
	v_cndmask_b32_e64 v21, v21, v23, s[10:11]
	v_mul_f32_e32 v22, 0x37800000, v21
	v_cndmask_b32_e32 v21, v21, v22, vcc
	v_cmp_class_f32_e32 vcc, v20, v165
	s_nop 1
	v_cndmask_b32_e32 v20, v21, v20, vcc
	v_div_scale_f32 v21, s[10:11], v20, v20, 1.0
	v_rcp_f32_e32 v22, v21
	v_div_scale_f32 v23, vcc, 1.0, v20, 1.0
	v_fma_f32 v24, -v21, v22, 1.0
	v_fmac_f32_e32 v22, v24, v22
	v_mul_f32_e32 v24, v23, v22
	v_fma_f32 v25, -v21, v24, v23
	v_fmac_f32_e32 v24, v25, v22
	v_fma_f32 v21, -v21, v24, v23
	v_div_fmas_f32 v21, v21, v22, v24
	v_div_fixup_f32 v20, v21, v20, 1.0
	s_and_b64 vcc, exec, s[8:9]
	v_pk_mul_f32 v[18:19], v[18:19], v[20:21] op_sel_hi:[1,0]
	v_pk_mul_f32 v[22:23], v[16:17], v[20:21] op_sel_hi:[1,0]
	v_pk_mul_f32 v[14:15], v[14:15], v[20:21] op_sel_hi:[1,0]
	v_pk_mul_f32 v[16:17], v[12:13], v[20:21] op_sel_hi:[1,0]
	s_cbranch_vccnz .LBB0_247
	v_mul_f32_e32 v21, 0xbfb8aa3b, v18
	v_exp_f32_e32 v21, v21
	v_mul_f32_e32 v12, 0xbfb8aa3b, v22
	v_mul_f32_e32 v13, 0xbfb8aa3b, v23
	v_exp_f32_e32 v12, v12
	v_add_f32_e32 v21, 1.0, v21
	v_rcp_f32_e32 v24, v21
	v_mul_f32_e32 v21, 0xbfb8aa3b, v19
	v_exp_f32_e32 v21, v21
	v_exp_f32_e32 v13, v13
	v_add_f32_e32 v12, 1.0, v12
	v_rcp_f32_e32 v12, v12
	v_add_f32_e32 v21, 1.0, v21
	v_rcp_f32_e32 v25, v21
	v_mul_f32_e32 v21, 0xbfb8aa3b, v14
	v_add_f32_e32 v13, 1.0, v13
	v_exp_f32_e32 v21, v21
	v_rcp_f32_e32 v13, v13
	v_pk_mul_f32 v[18:19], v[18:19], v[24:25]
	v_add_f32_e32 v21, 1.0, v21
	v_pk_mul_f32 v[22:23], v[22:23], v[12:13]
	v_mul_f32_e32 v12, 0xbfb8aa3b, v16
	v_mul_f32_e32 v13, 0xbfb8aa3b, v17
	v_rcp_f32_e32 v24, v21
	v_mul_f32_e32 v21, 0xbfb8aa3b, v15
	v_exp_f32_e32 v12, v12
	v_exp_f32_e32 v13, v13
	v_exp_f32_e32 v21, v21
	v_add_f32_e32 v12, 1.0, v12
	v_add_f32_e32 v13, 1.0, v13
	v_add_f32_e32 v21, 1.0, v21
	v_rcp_f32_e32 v12, v12
	v_rcp_f32_e32 v13, v13
	v_rcp_f32_e32 v25, v21
	v_pk_mul_f32 v[16:17], v[16:17], v[12:13]
	v_pk_mul_f32 v[14:15], v[14:15], v[24:25]

.LBB0_504:
	v_lshl_add_u32 v144, s82, 8, v154
	v_ashrrev_i32_e32 v145, 31, v144
	v_lshl_add_u64 v[146:147], v[144:145], 2, s[24:25]
	global_load_dword v240, v[146:147], off
	global_load_dword v241, v[146:147], off offset:64
	global_load_dword v242, v[146:147], off offset:128
	global_load_dword v243, v[146:147], off offset:192
	global_load_dword v244, v[146:147], off offset:512
	global_load_dword v245, v[146:147], off offset:576
	global_load_dword v246, v[146:147], off offset:640
	global_load_dword v247, v[146:147], off offset:704
	v_lshl_add_u32 v176, s2, 8, v157
	s_waitcnt vmcnt(0)
	v_fmamk_f32 v146, v240, 0x3a000000, v197
	v_cmp_gt_f32_e32 vcc, s36, v146
	v_mul_f32_e32 v147, 0x4f800000, v146
	s_nop 0
	v_cndmask_b32_e32 v146, v146, v147, vcc
	v_sqrt_f32_e32 v147, v146
	s_nop 0
	v_add_u32_e32 v148, -1, v147
	v_fma_f32 v149, -v148, v147, v146
	v_cmp_ge_f32_e64 s[10:11], 0, v149
	v_add_u32_e32 v149, 1, v147
	s_nop 0
	v_cndmask_b32_e64 v148, v147, v148, s[10:11]
	v_fma_f32 v147, -v149, v147, v146
	v_cmp_lt_f32_e64 s[10:11], 0, v147
	s_nop 1
	v_cndmask_b32_e64 v147, v148, v149, s[10:11]
	v_mul_f32_e32 v148, 0x37800000, v147
	v_cndmask_b32_e32 v147, v147, v148, vcc
	v_cmp_class_f32_e32 vcc, v146, v198
	s_nop 1
	v_cndmask_b32_e32 v146, v147, v146, vcc
	v_div_scale_f32 v147, s[2:3], v146, v146, 1.0
	v_rcp_f32_e32 v148, v147
	s_nop 0
	v_fma_f32 v149, -v147, v148, 1.0
	v_fmac_f32_e32 v148, v149, v148
	v_div_scale_f32 v149, vcc, 1.0, v146, 1.0
	v_mul_f32_e32 v150, v149, v148
	v_fma_f32 v151, -v147, v150, v149
	v_fmac_f32_e32 v150, v151, v148
	v_fma_f32 v147, -v147, v150, v149
	v_div_fmas_f32 v147, v147, v148, v150
	v_div_fixup_f32 v146, v147, v146, 1.0
	v_pk_mul_f32 v[124:125], v[124:125], v[146:147] op_sel_hi:[1,0]
	v_lshlrev_b64 v[148:149], 12, v[144:145]
	v_mul_f32_e32 v145, 0xbfb8aa3b, v124
	v_exp_f32_e32 v145, v145
	v_pk_mul_f32 v[126:127], v[126:127], v[146:147] op_sel_hi:[1,0]
	v_pk_mul_f32 v[120:121], v[120:121], v[146:147] op_sel_hi:[1,0]
	v_pk_mul_f32 v[122:123], v[122:123], v[146:147] op_sel_hi:[1,0]
	v_add_f32_e32 v145, 1.0, v145
	v_rcp_f32_e32 v145, v145
	s_nop 0
	v_mul_f32_e32 v124, v124, v145
	v_mul_f32_e32 v145, 0xbfb8aa3b, v125
	v_exp_f32_e32 v145, v145
	s_nop 0
	v_add_f32_e32 v145, 1.0, v145
	v_rcp_f32_e32 v145, v145
	s_nop 0
	v_mul_f32_e32 v125, v125, v145
	v_mul_f32_e32 v145, 0xbfb8aa3b, v126
	v_exp_f32_e32 v145, v145
	s_nop 0
	v_add_f32_e32 v145, 1.0, v145
	v_rcp_f32_e32 v145, v145
	s_nop 0
	v_mul_f32_e32 v126, v126, v145
	v_mul_f32_e32 v145, 0xbfb8aa3b, v127
	v_exp_f32_e32 v145, v145
	s_nop 0
	v_add_f32_e32 v145, 1.0, v145
	v_rcp_f32_e32 v145, v145
	s_nop 0
	v_mul_f32_e32 v127, v127, v145
	v_mul_f32_e32 v145, 0xbfb8aa3b, v120
	v_exp_f32_e32 v145, v145
	s_nop 0
	v_add_f32_e32 v145, 1.0, v145
	v_rcp_f32_e32 v145, v145
	s_nop 0
	v_mul_f32_e32 v145, v120, v145
	v_mul_f32_e32 v120, 0xbfb8aa3b, v121
	v_exp_f32_e32 v120, v120
	s_nop 0
	v_add_f32_e32 v120, 1.0, v120
	v_rcp_f32_e32 v120, v120
	s_nop 0
	v_mul_f32_e32 v147, v121, v120
	v_mul_f32_e32 v120, 0xbfb8aa3b, v122
	v_exp_f32_e32 v120, v120
	v_pk_mul_f32 v[116:117], v[116:117], v[146:147] op_sel_hi:[1,0]
	v_pk_mul_f32 v[118:119], v[118:119], v[146:147] op_sel_hi:[1,0]
	v_pk_mul_f32 v[112:113], v[112:113], v[146:147] op_sel_hi:[1,0]
	v_add_f32_e32 v120, 1.0, v120
	v_rcp_f32_e32 v120, v120
	v_pk_mul_f32 v[114:115], v[114:115], v[146:147] op_sel_hi:[1,0]
	v_mul_f32_e32 v150, v122, v120
	v_mul_f32_e32 v120, 0xbfb8aa3b, v123
	v_exp_f32_e32 v120, v120
	s_nop 0
	v_add_f32_e32 v120, 1.0, v120
	v_rcp_f32_e32 v120, v120
	s_nop 0
	v_mul_f32_e32 v123, v123, v120
	v_cvt_pk_bf16_f32 v120, v124, v125
	v_cvt_pk_bf16_f32 v121, v126, v127
	v_lshl_add_u64 v[126:127], s[22:23], 0, v[148:149]
	v_lshlrev_b64 v[124:125], 1, v[176:177]
	v_lshl_add_u64 v[126:127], v[126:127], 0, v[124:125]
	v_cvt_pk_bf16_f32 v122, v145, v147
	v_cvt_pk_bf16_f32 v123, v150, v123
	global_store_dwordx4 v[126:127], v[120:123], off
	s_nop 1
	v_mul_f32_e32 v120, 0xbfb8aa3b, v116
	v_exp_f32_e32 v120, v120
	s_nop 0
	v_add_f32_e32 v120, 1.0, v120
	v_rcp_f32_e32 v120, v120
	s_nop 0
	v_mul_f32_e32 v116, v116, v120
	v_mul_f32_e32 v120, 0xbfb8aa3b, v117
	v_exp_f32_e32 v120, v120
	s_nop 0
	v_add_f32_e32 v120, 1.0, v120
	v_rcp_f32_e32 v120, v120
	s_nop 0
	v_mul_f32_e32 v117, v117, v120
	v_mul_f32_e32 v120, 0xbfb8aa3b, v118
	v_exp_f32_e32 v120, v120
	s_nop 0
	v_add_f32_e32 v120, 1.0, v120
	v_rcp_f32_e32 v120, v120
	s_nop 0
	v_mul_f32_e32 v118, v118, v120
	v_mul_f32_e32 v120, 0xbfb8aa3b, v119
	v_exp_f32_e32 v120, v120
	s_nop 0
	v_add_f32_e32 v120, 1.0, v120
	v_rcp_f32_e32 v120, v120
	s_nop 0
	v_mul_f32_e32 v119, v119, v120
	v_mul_f32_e32 v120, 0xbfb8aa3b, v112
	v_exp_f32_e32 v120, v120
	s_nop 0
	v_add_f32_e32 v120, 1.0, v120
	v_rcp_f32_e32 v120, v120
	s_nop 0
	v_mul_f32_e32 v120, v112, v120
	v_mul_f32_e32 v112, 0xbfb8aa3b, v113
	v_exp_f32_e32 v112, v112
	s_nop 0
	v_add_f32_e32 v112, 1.0, v112
	v_rcp_f32_e32 v112, v112
	s_nop 0
	v_mul_f32_e32 v121, v113, v112
	v_mul_f32_e32 v112, 0xbfb8aa3b, v114
	v_exp_f32_e32 v112, v112
	s_nop 0
	v_add_f32_e32 v112, 1.0, v112
	v_rcp_f32_e32 v112, v112
	s_nop 0
	v_mul_f32_e32 v122, v114, v112
	v_mul_f32_e32 v112, 0xbfb8aa3b, v115
	v_exp_f32_e32 v112, v112
	s_nop 0
	v_add_f32_e32 v112, 1.0, v112
	v_rcp_f32_e32 v112, v112
	s_nop 0
	v_mul_f32_e32 v115, v115, v112
	v_cvt_pk_bf16_f32 v112, v116, v117
	v_cvt_pk_bf16_f32 v113, v118, v119
	v_cvt_pk_bf16_f32 v114, v120, v121
	v_cvt_pk_bf16_f32 v115, v122, v115
	global_store_dwordx4 v[126:127], v[112:115], off offset:256
	s_nop 1
	v_or_b32_e32 v114, 16, v144
	v_ashrrev_i32_e32 v115, 31, v114
	v_lshl_add_u64 v[112:113], v[114:115], 2, s[24:25]
	s_nop 0
	v_lshlrev_b64 v[114:115], 12, v[114:115]
	s_nop 0
	v_fmamk_f32 v112, v241, 0x3a000000, v197
	v_cmp_gt_f32_e32 vcc, s36, v112
	v_mul_f32_e32 v113, 0x4f800000, v112
	s_nop 0
	v_cndmask_b32_e32 v112, v112, v113, vcc
	v_sqrt_f32_e32 v113, v112
	s_nop 0
	v_add_u32_e32 v116, -1, v113
	v_fma_f32 v117, -v116, v113, v112
	v_cmp_ge_f32_e64 s[10:11], 0, v117
	v_add_u32_e32 v117, 1, v113
	s_nop 0
	v_cndmask_b32_e64 v116, v113, v116, s[10:11]
	v_fma_f32 v113, -v117, v113, v112
	v_cmp_lt_f32_e64 s[10:11], 0, v113
	s_nop 1
	v_cndmask_b32_e64 v113, v116, v117, s[10:11]
	v_mul_f32_e32 v116, 0x37800000, v113
	v_cndmask_b32_e32 v113, v113, v116, vcc
	v_cmp_class_f32_e32 vcc, v112, v198
	s_nop 1
	v_cndmask_b32_e32 v112, v113, v112, vcc
	v_div_scale_f32 v113, s[2:3], v112, v112, 1.0
	v_rcp_f32_e32 v116, v113
	s_nop 0
	v_fma_f32 v117, -v113, v116, 1.0
	v_fmac_f32_e32 v116, v117, v116
	v_div_scale_f32 v117, vcc, 1.0, v112, 1.0
	v_mul_f32_e32 v118, v117, v116
	v_fma_f32 v119, -v113, v118, v117
	v_fmac_f32_e32 v118, v119, v116
	v_fma_f32 v113, -v113, v118, v117
	v_div_fmas_f32 v113, v113, v116, v118
	v_div_fixup_f32 v112, v113, v112, 1.0
	v_pk_mul_f32 v[108:109], v[108:109], v[112:113] op_sel_hi:[1,0]
	v_pk_mul_f32 v[110:111], v[110:111], v[112:113] op_sel_hi:[1,0]
	v_mul_f32_e32 v113, 0xbfb8aa3b, v108
	v_exp_f32_e32 v113, v113
	s_nop 0
	v_add_f32_e32 v113, 1.0, v113
	v_rcp_f32_e32 v113, v113
	s_nop 0
	v_mul_f32_e32 v108, v108, v113
	v_mul_f32_e32 v113, 0xbfb8aa3b, v109
	v_exp_f32_e32 v113, v113
	s_nop 0
	v_add_f32_e32 v113, 1.0, v113
	v_rcp_f32_e32 v113, v113
	s_nop 0
	v_mul_f32_e32 v109, v109, v113
	v_mul_f32_e32 v113, 0xbfb8aa3b, v110
	v_exp_f32_e32 v113, v113
	s_nop 0
	v_add_f32_e32 v113, 1.0, v113
	v_rcp_f32_e32 v113, v113
	s_nop 0
	v_mul_f32_e32 v110, v110, v113
	v_mul_f32_e32 v113, 0xbfb8aa3b, v111
	v_exp_f32_e32 v113, v113
	s_nop 0
	v_add_f32_e32 v113, 1.0, v113
	v_rcp_f32_e32 v113, v113
	s_nop 0
	v_pk_mul_f32 v[104:105], v[104:105], v[112:113] op_sel_hi:[1,0]
	v_mul_f32_e32 v111, v111, v113
	v_pk_mul_f32 v[106:107], v[106:107], v[112:113] op_sel_hi:[1,0]
	v_mul_f32_e32 v113, 0xbfb8aa3b, v104
	v_exp_f32_e32 v113, v113
	s_nop 0
	v_add_f32_e32 v113, 1.0, v113
	v_rcp_f32_e32 v113, v113
	s_nop 0
	v_mul_f32_e32 v113, v104, v113
	v_mul_f32_e32 v104, 0xbfb8aa3b, v105
	v_exp_f32_e32 v104, v104
	v_pk_mul_f32 v[100:101], v[100:101], v[112:113] op_sel_hi:[1,0]
	v_pk_mul_f32 v[102:103], v[102:103], v[112:113] op_sel_hi:[1,0]
	v_pk_mul_f32 v[96:97], v[96:97], v[112:113] op_sel_hi:[1,0]
	v_add_f32_e32 v104, 1.0, v104
	v_rcp_f32_e32 v104, v104
	v_pk_mul_f32 v[98:99], v[98:99], v[112:113] op_sel_hi:[1,0]
	v_mul_f32_e32 v116, v105, v104
	v_mul_f32_e32 v104, 0xbfb8aa3b, v106
	v_exp_f32_e32 v104, v104
	s_nop 0
	v_add_f32_e32 v104, 1.0, v104
	v_rcp_f32_e32 v104, v104
	s_nop 0
	v_mul_f32_e32 v117, v106, v104
	v_mul_f32_e32 v104, 0xbfb8aa3b, v107
	v_exp_f32_e32 v104, v104
	s_nop 0
	v_add_f32_e32 v104, 1.0, v104
	v_rcp_f32_e32 v104, v104
	s_nop 0
	v_mul_f32_e32 v107, v107, v104
	v_cvt_pk_bf16_f32 v104, v108, v109
	v_lshl_add_u64 v[108:109], s[22:23], 0, v[114:115]
	v_lshl_add_u64 v[108:109], v[108:109], 0, v[124:125]
	v_cvt_pk_bf16_f32 v105, v110, v111
	v_cvt_pk_bf16_f32 v106, v113, v116
	v_cvt_pk_bf16_f32 v107, v117, v107
	global_store_dwordx4 v[108:109], v[104:107], off
	s_nop 1
	v_mul_f32_e32 v104, 0xbfb8aa3b, v100
	v_exp_f32_e32 v104, v104
	s_nop 0
	v_add_f32_e32 v104, 1.0, v104
	v_rcp_f32_e32 v104, v104
	s_nop 0
	v_mul_f32_e32 v100, v100, v104
	v_mul_f32_e32 v104, 0xbfb8aa3b, v101
	v_exp_f32_e32 v104, v104
	s_nop 0
	v_add_f32_e32 v104, 1.0, v104
	v_rcp_f32_e32 v104, v104
	s_nop 0
	v_mul_f32_e32 v101, v101, v104
	v_mul_f32_e32 v104, 0xbfb8aa3b, v102
	v_exp_f32_e32 v104, v104
	s_nop 0
	v_add_f32_e32 v104, 1.0, v104
	v_rcp_f32_e32 v104, v104
	s_nop 0
	v_mul_f32_e32 v102, v102, v104
	v_mul_f32_e32 v104, 0xbfb8aa3b, v103
	v_exp_f32_e32 v104, v104
	s_nop 0
	v_add_f32_e32 v104, 1.0, v104
	v_rcp_f32_e32 v104, v104
	s_nop 0
	v_mul_f32_e32 v103, v103, v104
	v_mul_f32_e32 v104, 0xbfb8aa3b, v96
	v_exp_f32_e32 v104, v104
	s_nop 0
	v_add_f32_e32 v104, 1.0, v104
	v_rcp_f32_e32 v104, v104
	s_nop 0
	v_mul_f32_e32 v104, v96, v104
	v_mul_f32_e32 v96, 0xbfb8aa3b, v97
	v_exp_f32_e32 v96, v96
	s_nop 0
	v_add_f32_e32 v96, 1.0, v96
	v_rcp_f32_e32 v96, v96
	s_nop 0
	v_mul_f32_e32 v105, v97, v96
	v_mul_f32_e32 v96, 0xbfb8aa3b, v98
	v_exp_f32_e32 v96, v96
	s_nop 0
	v_add_f32_e32 v96, 1.0, v96
	v_rcp_f32_e32 v96, v96
	s_nop 0
	v_mul_f32_e32 v106, v98, v96
	v_mul_f32_e32 v96, 0xbfb8aa3b, v99
	v_exp_f32_e32 v96, v96
	s_nop 0
	v_add_f32_e32 v96, 1.0, v96
	v_rcp_f32_e32 v96, v96
	s_nop 0
	v_mul_f32_e32 v99, v99, v96
	v_cvt_pk_bf16_f32 v96, v100, v101
	v_cvt_pk_bf16_f32 v97, v102, v103
	v_cvt_pk_bf16_f32 v98, v104, v105
	v_cvt_pk_bf16_f32 v99, v106, v99
	global_store_dwordx4 v[108:109], v[96:99], off offset:256
	s_nop 1
	v_or_b32_e32 v98, 32, v144
	v_ashrrev_i32_e32 v99, 31, v98
	v_lshl_add_u64 v[96:97], v[98:99], 2, s[24:25]
	s_nop 0
	v_lshlrev_b64 v[98:99], 12, v[98:99]
	s_nop 0
	v_fmamk_f32 v96, v242, 0x3a000000, v197
	v_cmp_gt_f32_e32 vcc, s36, v96
	v_mul_f32_e32 v97, 0x4f800000, v96
	s_nop 0
	v_cndmask_b32_e32 v96, v96, v97, vcc
	v_sqrt_f32_e32 v97, v96
	s_nop 0
	v_add_u32_e32 v100, -1, v97
	v_fma_f32 v101, -v100, v97, v96
	v_cmp_ge_f32_e64 s[10:11], 0, v101
	v_add_u32_e32 v101, 1, v97
	s_nop 0
	v_cndmask_b32_e64 v100, v97, v100, s[10:11]
	v_fma_f32 v97, -v101, v97, v96
	v_cmp_lt_f32_e64 s[10:11], 0, v97
	s_nop 1
	v_cndmask_b32_e64 v97, v100, v101, s[10:11]
	v_mul_f32_e32 v100, 0x37800000, v97
	v_cndmask_b32_e32 v97, v97, v100, vcc
	v_cmp_class_f32_e32 vcc, v96, v198
	s_nop 1
	v_cndmask_b32_e32 v96, v97, v96, vcc
	v_div_scale_f32 v97, s[2:3], v96, v96, 1.0
	v_rcp_f32_e32 v100, v97
	s_nop 0
	v_fma_f32 v101, -v97, v100, 1.0
	v_fmac_f32_e32 v100, v101, v100
	v_div_scale_f32 v101, vcc, 1.0, v96, 1.0
	v_mul_f32_e32 v102, v101, v100
	v_fma_f32 v103, -v97, v102, v101
	v_fmac_f32_e32 v102, v103, v100
	v_fma_f32 v97, -v97, v102, v101
	v_div_fmas_f32 v97, v97, v100, v102
	v_div_fixup_f32 v96, v97, v96, 1.0
	v_pk_mul_f32 v[92:93], v[92:93], v[96:97] op_sel_hi:[1,0]
	v_pk_mul_f32 v[94:95], v[94:95], v[96:97] op_sel_hi:[1,0]
	v_mul_f32_e32 v97, 0xbfb8aa3b, v92
	v_exp_f32_e32 v97, v97
	s_nop 0
	v_add_f32_e32 v97, 1.0, v97
	v_rcp_f32_e32 v97, v97
	s_nop 0
	v_mul_f32_e32 v92, v92, v97
	v_mul_f32_e32 v97, 0xbfb8aa3b, v93
	v_exp_f32_e32 v97, v97
	s_nop 0
	v_add_f32_e32 v97, 1.0, v97
	v_rcp_f32_e32 v97, v97
	s_nop 0
	v_mul_f32_e32 v93, v93, v97
	v_mul_f32_e32 v97, 0xbfb8aa3b, v94
	v_exp_f32_e32 v97, v97
	s_nop 0
	v_add_f32_e32 v97, 1.0, v97
	v_rcp_f32_e32 v97, v97
	s_nop 0
	v_mul_f32_e32 v94, v94, v97
	v_mul_f32_e32 v97, 0xbfb8aa3b, v95
	v_exp_f32_e32 v97, v97
	s_nop 0
	v_add_f32_e32 v97, 1.0, v97
	v_rcp_f32_e32 v97, v97
	s_nop 0
	v_pk_mul_f32 v[88:89], v[88:89], v[96:97] op_sel_hi:[1,0]
	v_mul_f32_e32 v95, v95, v97
	v_pk_mul_f32 v[90:91], v[90:91], v[96:97] op_sel_hi:[1,0]
	v_mul_f32_e32 v97, 0xbfb8aa3b, v88
	v_exp_f32_e32 v97, v97
	s_nop 0
	v_add_f32_e32 v97, 1.0, v97
	v_rcp_f32_e32 v97, v97
	s_nop 0
	v_mul_f32_e32 v97, v88, v97
	v_mul_f32_e32 v88, 0xbfb8aa3b, v89
	v_exp_f32_e32 v88, v88
	v_pk_mul_f32 v[84:85], v[84:85], v[96:97] op_sel_hi:[1,0]
	v_pk_mul_f32 v[86:87], v[86:87], v[96:97] op_sel_hi:[1,0]
	v_pk_mul_f32 v[80:81], v[80:81], v[96:97] op_sel_hi:[1,0]
	v_add_f32_e32 v88, 1.0, v88
	v_rcp_f32_e32 v88, v88
	v_pk_mul_f32 v[82:83], v[82:83], v[96:97] op_sel_hi:[1,0]
	v_mul_f32_e32 v100, v89, v88
	v_mul_f32_e32 v88, 0xbfb8aa3b, v90
	v_exp_f32_e32 v88, v88
	s_nop 0
	v_add_f32_e32 v88, 1.0, v88
	v_rcp_f32_e32 v88, v88
	s_nop 0
	v_mul_f32_e32 v101, v90, v88
	v_mul_f32_e32 v88, 0xbfb8aa3b, v91
	v_exp_f32_e32 v88, v88
	s_nop 0
	v_add_f32_e32 v88, 1.0, v88
	v_rcp_f32_e32 v88, v88
	s_nop 0
	v_mul_f32_e32 v91, v91, v88
	v_cvt_pk_bf16_f32 v88, v92, v93
	v_lshl_add_u64 v[92:93], s[22:23], 0, v[98:99]
	v_lshl_add_u64 v[92:93], v[92:93], 0, v[124:125]
	v_cvt_pk_bf16_f32 v89, v94, v95
	v_cvt_pk_bf16_f32 v90, v97, v100
	v_cvt_pk_bf16_f32 v91, v101, v91
	global_store_dwordx4 v[92:93], v[88:91], off
	s_nop 1
	v_mul_f32_e32 v88, 0xbfb8aa3b, v84
	v_exp_f32_e32 v88, v88
	s_nop 0
	v_add_f32_e32 v88, 1.0, v88
	v_rcp_f32_e32 v88, v88
	s_nop 0
	v_mul_f32_e32 v84, v84, v88
	v_mul_f32_e32 v88, 0xbfb8aa3b, v85
	v_exp_f32_e32 v88, v88
	s_nop 0
	v_add_f32_e32 v88, 1.0, v88
	v_rcp_f32_e32 v88, v88
	s_nop 0
	v_mul_f32_e32 v85, v85, v88
	v_mul_f32_e32 v88, 0xbfb8aa3b, v86
	v_exp_f32_e32 v88, v88
	s_nop 0
	v_add_f32_e32 v88, 1.0, v88
	v_rcp_f32_e32 v88, v88
	s_nop 0
	v_mul_f32_e32 v86, v86, v88
	v_mul_f32_e32 v88, 0xbfb8aa3b, v87
	v_exp_f32_e32 v88, v88
	s_nop 0
	v_add_f32_e32 v88, 1.0, v88
	v_rcp_f32_e32 v88, v88
	s_nop 0
	v_mul_f32_e32 v87, v87, v88
	v_mul_f32_e32 v88, 0xbfb8aa3b, v80
	v_exp_f32_e32 v88, v88
	s_nop 0
	v_add_f32_e32 v88, 1.0, v88
	v_rcp_f32_e32 v88, v88
	s_nop 0
	v_mul_f32_e32 v88, v80, v88
	v_mul_f32_e32 v80, 0xbfb8aa3b, v81
	v_exp_f32_e32 v80, v80
	s_nop 0
	v_add_f32_e32 v80, 1.0, v80
	v_rcp_f32_e32 v80, v80
	s_nop 0
	v_mul_f32_e32 v89, v81, v80
	v_mul_f32_e32 v80, 0xbfb8aa3b, v82
	v_exp_f32_e32 v80, v80
	s_nop 0
	v_add_f32_e32 v80, 1.0, v80
	v_rcp_f32_e32 v80, v80
	s_nop 0
	v_mul_f32_e32 v90, v82, v80
	v_mul_f32_e32 v80, 0xbfb8aa3b, v83
	v_exp_f32_e32 v80, v80
	s_nop 0
	v_add_f32_e32 v80, 1.0, v80
	v_rcp_f32_e32 v80, v80
	s_nop 0
	v_mul_f32_e32 v83, v83, v80
	v_cvt_pk_bf16_f32 v80, v84, v85
	v_cvt_pk_bf16_f32 v81, v86, v87
	v_cvt_pk_bf16_f32 v82, v88, v89
	v_cvt_pk_bf16_f32 v83, v90, v83
	global_store_dwordx4 v[92:93], v[80:83], off offset:256
	s_nop 1
	v_or_b32_e32 v82, 48, v144
	v_ashrrev_i32_e32 v83, 31, v82
	v_lshl_add_u64 v[80:81], v[82:83], 2, s[24:25]
	s_nop 0
	v_lshlrev_b64 v[82:83], 12, v[82:83]
	s_nop 0
	v_fmamk_f32 v80, v243, 0x3a000000, v197
	v_cmp_gt_f32_e32 vcc, s36, v80
	v_mul_f32_e32 v81, 0x4f800000, v80
	s_nop 0
	v_cndmask_b32_e32 v80, v80, v81, vcc
	v_sqrt_f32_e32 v81, v80
	s_nop 0
	v_add_u32_e32 v84, -1, v81
	v_fma_f32 v85, -v84, v81, v80
	v_cmp_ge_f32_e64 s[10:11], 0, v85
	v_add_u32_e32 v85, 1, v81
	s_nop 0
	v_cndmask_b32_e64 v84, v81, v84, s[10:11]
	v_fma_f32 v81, -v85, v81, v80
	v_cmp_lt_f32_e64 s[10:11], 0, v81
	s_nop 1
	v_cndmask_b32_e64 v81, v84, v85, s[10:11]
	v_mul_f32_e32 v84, 0x37800000, v81
	v_cndmask_b32_e32 v81, v81, v84, vcc
	v_cmp_class_f32_e32 vcc, v80, v198
	s_nop 1
	v_cndmask_b32_e32 v80, v81, v80, vcc
	v_div_scale_f32 v81, s[2:3], v80, v80, 1.0
	v_rcp_f32_e32 v84, v81
	s_nop 0
	v_fma_f32 v85, -v81, v84, 1.0
	v_fmac_f32_e32 v84, v85, v84
	v_div_scale_f32 v85, vcc, 1.0, v80, 1.0
	v_mul_f32_e32 v86, v85, v84
	v_fma_f32 v87, -v81, v86, v85
	v_fmac_f32_e32 v86, v87, v84
	v_fma_f32 v81, -v81, v86, v85
	v_div_fmas_f32 v81, v81, v84, v86
	v_div_fixup_f32 v80, v81, v80, 1.0
	v_pk_mul_f32 v[76:77], v[76:77], v[80:81] op_sel_hi:[1,0]
	v_pk_mul_f32 v[78:79], v[78:79], v[80:81] op_sel_hi:[1,0]
	v_mul_f32_e32 v81, 0xbfb8aa3b, v76
	v_exp_f32_e32 v81, v81
	s_nop 0
	v_add_f32_e32 v81, 1.0, v81
	v_rcp_f32_e32 v81, v81
	s_nop 0
	v_mul_f32_e32 v76, v76, v81
	v_mul_f32_e32 v81, 0xbfb8aa3b, v77
	v_exp_f32_e32 v81, v81
	s_nop 0
	v_add_f32_e32 v81, 1.0, v81
	v_rcp_f32_e32 v81, v81
	s_nop 0
	v_mul_f32_e32 v77, v77, v81
	v_mul_f32_e32 v81, 0xbfb8aa3b, v78
	v_exp_f32_e32 v81, v81
	s_nop 0
	v_add_f32_e32 v81, 1.0, v81
	v_rcp_f32_e32 v81, v81
	s_nop 0
	v_mul_f32_e32 v78, v78, v81
	v_mul_f32_e32 v81, 0xbfb8aa3b, v79
	v_exp_f32_e32 v81, v81
	s_nop 0
	v_add_f32_e32 v81, 1.0, v81
	v_rcp_f32_e32 v81, v81
	s_nop 0
	v_pk_mul_f32 v[72:73], v[72:73], v[80:81] op_sel_hi:[1,0]
	v_mul_f32_e32 v79, v79, v81
	v_pk_mul_f32 v[74:75], v[74:75], v[80:81] op_sel_hi:[1,0]
	v_mul_f32_e32 v81, 0xbfb8aa3b, v72
	v_exp_f32_e32 v81, v81
	s_nop 0
	v_add_f32_e32 v81, 1.0, v81
	v_rcp_f32_e32 v81, v81
	s_nop 0
	v_mul_f32_e32 v81, v72, v81
	v_mul_f32_e32 v72, 0xbfb8aa3b, v73
	v_exp_f32_e32 v72, v72
	v_pk_mul_f32 v[68:69], v[68:69], v[80:81] op_sel_hi:[1,0]
	v_pk_mul_f32 v[70:71], v[70:71], v[80:81] op_sel_hi:[1,0]
	v_pk_mul_f32 v[64:65], v[64:65], v[80:81] op_sel_hi:[1,0]
	v_add_f32_e32 v72, 1.0, v72
	v_rcp_f32_e32 v72, v72
	v_pk_mul_f32 v[66:67], v[66:67], v[80:81] op_sel_hi:[1,0]
	v_mul_f32_e32 v84, v73, v72
	v_mul_f32_e32 v72, 0xbfb8aa3b, v74
	v_exp_f32_e32 v72, v72
	s_nop 0
	v_add_f32_e32 v72, 1.0, v72
	v_rcp_f32_e32 v72, v72
	s_nop 0
	v_mul_f32_e32 v85, v74, v72
	v_mul_f32_e32 v72, 0xbfb8aa3b, v75
	v_exp_f32_e32 v72, v72
	s_nop 0
	v_add_f32_e32 v72, 1.0, v72
	v_rcp_f32_e32 v72, v72
	s_nop 0
	v_mul_f32_e32 v75, v75, v72
	v_cvt_pk_bf16_f32 v72, v76, v77
	v_lshl_add_u64 v[76:77], s[22:23], 0, v[82:83]
	v_lshl_add_u64 v[76:77], v[76:77], 0, v[124:125]
	v_cvt_pk_bf16_f32 v73, v78, v79
	v_cvt_pk_bf16_f32 v74, v81, v84
	v_cvt_pk_bf16_f32 v75, v85, v75
	global_store_dwordx4 v[76:77], v[72:75], off
	s_nop 1
	v_mul_f32_e32 v72, 0xbfb8aa3b, v68
	v_exp_f32_e32 v72, v72
	s_nop 0
	v_add_f32_e32 v72, 1.0, v72
	v_rcp_f32_e32 v72, v72
	s_nop 0
	v_mul_f32_e32 v68, v68, v72
	v_mul_f32_e32 v72, 0xbfb8aa3b, v69
	v_exp_f32_e32 v72, v72
	s_nop 0
	v_add_f32_e32 v72, 1.0, v72
	v_rcp_f32_e32 v72, v72
	s_nop 0
	v_mul_f32_e32 v69, v69, v72
	v_mul_f32_e32 v72, 0xbfb8aa3b, v70
	v_exp_f32_e32 v72, v72
	s_nop 0
	v_add_f32_e32 v72, 1.0, v72
	v_rcp_f32_e32 v72, v72
	s_nop 0
	v_mul_f32_e32 v70, v70, v72
	v_mul_f32_e32 v72, 0xbfb8aa3b, v71
	v_exp_f32_e32 v72, v72
	s_nop 0
	v_add_f32_e32 v72, 1.0, v72
	v_rcp_f32_e32 v72, v72
	s_nop 0
	v_mul_f32_e32 v71, v71, v72
	v_mul_f32_e32 v72, 0xbfb8aa3b, v64
	v_exp_f32_e32 v72, v72
	s_nop 0
	v_add_f32_e32 v72, 1.0, v72
	v_rcp_f32_e32 v72, v72
	s_nop 0
	v_mul_f32_e32 v72, v64, v72
	v_mul_f32_e32 v64, 0xbfb8aa3b, v65
	v_exp_f32_e32 v64, v64
	s_nop 0
	v_add_f32_e32 v64, 1.0, v64
	v_rcp_f32_e32 v64, v64
	s_nop 0
	v_mul_f32_e32 v73, v65, v64
	v_mul_f32_e32 v64, 0xbfb8aa3b, v66
	v_exp_f32_e32 v64, v64
	s_nop 0
	v_add_f32_e32 v64, 1.0, v64
	v_rcp_f32_e32 v64, v64
	s_nop 0
	v_mul_f32_e32 v74, v66, v64
	v_mul_f32_e32 v64, 0xbfb8aa3b, v67
	v_exp_f32_e32 v64, v64
	s_nop 0
	v_add_f32_e32 v64, 1.0, v64
	v_rcp_f32_e32 v64, v64
	s_nop 0
	v_mul_f32_e32 v67, v67, v64
	v_cvt_pk_bf16_f32 v64, v68, v69
	v_cvt_pk_bf16_f32 v65, v70, v71
	v_cvt_pk_bf16_f32 v66, v72, v73
	v_cvt_pk_bf16_f32 v67, v74, v67
	global_store_dwordx4 v[76:77], v[64:67], off offset:256
	s_nop 1
	v_add_u32_e32 v66, 0x80, v144
	v_ashrrev_i32_e32 v67, 31, v66
	v_lshl_add_u64 v[64:65], v[66:67], 2, s[24:25]
	s_nop 0
	v_lshlrev_b64 v[66:67], 12, v[66:67]
	s_nop 0
	v_fmamk_f32 v64, v244, 0x3a000000, v197
	v_cmp_gt_f32_e32 vcc, s36, v64
	v_mul_f32_e32 v65, 0x4f800000, v64
	s_nop 0
	v_cndmask_b32_e32 v64, v64, v65, vcc
	v_sqrt_f32_e32 v65, v64
	s_nop 0
	v_add_u32_e32 v68, -1, v65
	v_fma_f32 v69, -v68, v65, v64
	v_cmp_ge_f32_e64 s[10:11], 0, v69
	v_add_u32_e32 v69, 1, v65
	s_nop 0
	v_cndmask_b32_e64 v68, v65, v68, s[10:11]
	v_fma_f32 v65, -v69, v65, v64
	v_cmp_lt_f32_e64 s[10:11], 0, v65
	s_nop 1
	v_cndmask_b32_e64 v65, v68, v69, s[10:11]
	v_mul_f32_e32 v68, 0x37800000, v65
	v_cndmask_b32_e32 v65, v65, v68, vcc
	v_cmp_class_f32_e32 vcc, v64, v198
	s_nop 1
	v_cndmask_b32_e32 v64, v65, v64, vcc
	v_div_scale_f32 v65, s[2:3], v64, v64, 1.0
	v_rcp_f32_e32 v68, v65
	s_nop 0
	v_fma_f32 v69, -v65, v68, 1.0
	v_fmac_f32_e32 v68, v69, v68
	v_div_scale_f32 v69, vcc, 1.0, v64, 1.0
	v_mul_f32_e32 v70, v69, v68
	v_fma_f32 v71, -v65, v70, v69
	v_fmac_f32_e32 v70, v71, v68
	v_fma_f32 v65, -v65, v70, v69
	v_div_fmas_f32 v65, v65, v68, v70
	v_div_fixup_f32 v64, v65, v64, 1.0
	v_pk_mul_f32 v[60:61], v[60:61], v[64:65] op_sel_hi:[1,0]
	v_pk_mul_f32 v[62:63], v[62:63], v[64:65] op_sel_hi:[1,0]
	v_mul_f32_e32 v65, 0xbfb8aa3b, v60
	v_exp_f32_e32 v65, v65
	s_nop 0
	v_add_f32_e32 v65, 1.0, v65
	v_rcp_f32_e32 v65, v65
	s_nop 0
	v_mul_f32_e32 v60, v60, v65
	v_mul_f32_e32 v65, 0xbfb8aa3b, v61
	v_exp_f32_e32 v65, v65
	s_nop 0
	v_add_f32_e32 v65, 1.0, v65
	v_rcp_f32_e32 v65, v65
	s_nop 0
	v_mul_f32_e32 v61, v61, v65
	v_mul_f32_e32 v65, 0xbfb8aa3b, v62
	v_exp_f32_e32 v65, v65
	s_nop 0
	v_add_f32_e32 v65, 1.0, v65
	v_rcp_f32_e32 v65, v65
	s_nop 0
	v_mul_f32_e32 v62, v62, v65
	v_mul_f32_e32 v65, 0xbfb8aa3b, v63
	v_exp_f32_e32 v65, v65
	s_nop 0
	v_add_f32_e32 v65, 1.0, v65
	v_rcp_f32_e32 v65, v65
	s_nop 0
	v_pk_mul_f32 v[56:57], v[56:57], v[64:65] op_sel_hi:[1,0]
	v_mul_f32_e32 v63, v63, v65
	v_pk_mul_f32 v[58:59], v[58:59], v[64:65] op_sel_hi:[1,0]
	v_mul_f32_e32 v65, 0xbfb8aa3b, v56
	v_exp_f32_e32 v65, v65
	s_nop 0
	v_add_f32_e32 v65, 1.0, v65
	v_rcp_f32_e32 v65, v65
	s_nop 0
	v_mul_f32_e32 v65, v56, v65
	v_mul_f32_e32 v56, 0xbfb8aa3b, v57
	v_exp_f32_e32 v56, v56
	v_pk_mul_f32 v[52:53], v[52:53], v[64:65] op_sel_hi:[1,0]
	v_pk_mul_f32 v[54:55], v[54:55], v[64:65] op_sel_hi:[1,0]
	v_pk_mul_f32 v[48:49], v[48:49], v[64:65] op_sel_hi:[1,0]
	v_add_f32_e32 v56, 1.0, v56
	v_rcp_f32_e32 v56, v56
	v_pk_mul_f32 v[50:51], v[50:51], v[64:65] op_sel_hi:[1,0]
	v_mul_f32_e32 v68, v57, v56
	v_mul_f32_e32 v56, 0xbfb8aa3b, v58
	v_exp_f32_e32 v56, v56
	s_nop 0
	v_add_f32_e32 v56, 1.0, v56
	v_rcp_f32_e32 v56, v56
	s_nop 0
	v_mul_f32_e32 v69, v58, v56
	v_mul_f32_e32 v56, 0xbfb8aa3b, v59
	v_exp_f32_e32 v56, v56
	s_nop 0
	v_add_f32_e32 v56, 1.0, v56
	v_rcp_f32_e32 v56, v56
	s_nop 0
	v_mul_f32_e32 v59, v59, v56
	v_cvt_pk_bf16_f32 v56, v60, v61
	v_lshl_add_u64 v[60:61], s[22:23], 0, v[66:67]
	v_lshl_add_u64 v[60:61], v[60:61], 0, v[124:125]
	v_cvt_pk_bf16_f32 v57, v62, v63
	v_cvt_pk_bf16_f32 v58, v65, v68
	v_cvt_pk_bf16_f32 v59, v69, v59
	global_store_dwordx4 v[60:61], v[56:59], off
	s_nop 1
	v_mul_f32_e32 v56, 0xbfb8aa3b, v52
	v_exp_f32_e32 v56, v56
	s_nop 0
	v_add_f32_e32 v56, 1.0, v56
	v_rcp_f32_e32 v56, v56
	s_nop 0
	v_mul_f32_e32 v52, v52, v56
	v_mul_f32_e32 v56, 0xbfb8aa3b, v53
	v_exp_f32_e32 v56, v56
	s_nop 0
	v_add_f32_e32 v56, 1.0, v56
	v_rcp_f32_e32 v56, v56
	s_nop 0
	v_mul_f32_e32 v53, v53, v56
	v_mul_f32_e32 v56, 0xbfb8aa3b, v54
	v_exp_f32_e32 v56, v56
	s_nop 0
	v_add_f32_e32 v56, 1.0, v56
	v_rcp_f32_e32 v56, v56
	s_nop 0
	v_mul_f32_e32 v54, v54, v56
	v_mul_f32_e32 v56, 0xbfb8aa3b, v55
	v_exp_f32_e32 v56, v56
	s_nop 0
	v_add_f32_e32 v56, 1.0, v56
	v_rcp_f32_e32 v56, v56
	s_nop 0
	v_mul_f32_e32 v55, v55, v56
	v_mul_f32_e32 v56, 0xbfb8aa3b, v48
	v_exp_f32_e32 v56, v56
	s_nop 0
	v_add_f32_e32 v56, 1.0, v56
	v_rcp_f32_e32 v56, v56
	s_nop 0
	v_mul_f32_e32 v56, v48, v56
	v_mul_f32_e32 v48, 0xbfb8aa3b, v49
	v_exp_f32_e32 v48, v48
	s_nop 0
	v_add_f32_e32 v48, 1.0, v48
	v_rcp_f32_e32 v48, v48
	s_nop 0
	v_mul_f32_e32 v57, v49, v48
	v_mul_f32_e32 v48, 0xbfb8aa3b, v50
	v_exp_f32_e32 v48, v48
	s_nop 0
	v_add_f32_e32 v48, 1.0, v48
	v_rcp_f32_e32 v48, v48
	s_nop 0
	v_mul_f32_e32 v58, v50, v48
	v_mul_f32_e32 v48, 0xbfb8aa3b, v51
	v_exp_f32_e32 v48, v48
	s_nop 0
	v_add_f32_e32 v48, 1.0, v48
	v_rcp_f32_e32 v48, v48
	s_nop 0
	v_mul_f32_e32 v51, v51, v48
	v_cvt_pk_bf16_f32 v48, v52, v53
	v_cvt_pk_bf16_f32 v49, v54, v55
	v_cvt_pk_bf16_f32 v50, v56, v57
	v_cvt_pk_bf16_f32 v51, v58, v51
	global_store_dwordx4 v[60:61], v[48:51], off offset:256
	s_nop 1
	v_add_u32_e32 v50, 0x90, v144
	v_ashrrev_i32_e32 v51, 31, v50
	v_lshl_add_u64 v[48:49], v[50:51], 2, s[24:25]
	s_nop 0
	v_lshlrev_b64 v[50:51], 12, v[50:51]
	s_nop 0
	v_fmamk_f32 v48, v245, 0x3a000000, v197
	v_cmp_gt_f32_e32 vcc, s36, v48
	v_mul_f32_e32 v49, 0x4f800000, v48
	s_nop 0
	v_cndmask_b32_e32 v48, v48, v49, vcc
	v_sqrt_f32_e32 v49, v48
	s_nop 0
	v_add_u32_e32 v52, -1, v49
	v_fma_f32 v53, -v52, v49, v48
	v_cmp_ge_f32_e64 s[10:11], 0, v53
	v_add_u32_e32 v53, 1, v49
	s_nop 0
	v_cndmask_b32_e64 v52, v49, v52, s[10:11]
	v_fma_f32 v49, -v53, v49, v48
	v_cmp_lt_f32_e64 s[10:11], 0, v49
	s_nop 1
	v_cndmask_b32_e64 v49, v52, v53, s[10:11]
	v_mul_f32_e32 v52, 0x37800000, v49
	v_cndmask_b32_e32 v49, v49, v52, vcc
	v_cmp_class_f32_e32 vcc, v48, v198
	s_nop 1
	v_cndmask_b32_e32 v48, v49, v48, vcc
	v_div_scale_f32 v49, s[2:3], v48, v48, 1.0
	v_rcp_f32_e32 v52, v49
	s_nop 0
	v_fma_f32 v53, -v49, v52, 1.0
	v_fmac_f32_e32 v52, v53, v52
	v_div_scale_f32 v53, vcc, 1.0, v48, 1.0
	v_mul_f32_e32 v54, v53, v52
	v_fma_f32 v55, -v49, v54, v53
	v_fmac_f32_e32 v54, v55, v52
	v_fma_f32 v49, -v49, v54, v53
	v_div_fmas_f32 v49, v49, v52, v54
	v_div_fixup_f32 v48, v49, v48, 1.0
	v_pk_mul_f32 v[44:45], v[44:45], v[48:49] op_sel_hi:[1,0]
	v_pk_mul_f32 v[46:47], v[46:47], v[48:49] op_sel_hi:[1,0]
	v_mul_f32_e32 v49, 0xbfb8aa3b, v44
	v_exp_f32_e32 v49, v49
	s_nop 0
	v_add_f32_e32 v49, 1.0, v49
	v_rcp_f32_e32 v49, v49
	s_nop 0
	v_mul_f32_e32 v44, v44, v49
	v_mul_f32_e32 v49, 0xbfb8aa3b, v45
	v_exp_f32_e32 v49, v49
	s_nop 0
	v_add_f32_e32 v49, 1.0, v49
	v_rcp_f32_e32 v49, v49
	s_nop 0
	v_mul_f32_e32 v45, v45, v49
	v_mul_f32_e32 v49, 0xbfb8aa3b, v46
	v_exp_f32_e32 v49, v49
	s_nop 0
	v_add_f32_e32 v49, 1.0, v49
	v_rcp_f32_e32 v49, v49
	s_nop 0
	v_mul_f32_e32 v46, v46, v49
	v_mul_f32_e32 v49, 0xbfb8aa3b, v47
	v_exp_f32_e32 v49, v49
	s_nop 0
	v_add_f32_e32 v49, 1.0, v49
	v_rcp_f32_e32 v49, v49
	s_nop 0
	v_pk_mul_f32 v[40:41], v[40:41], v[48:49] op_sel_hi:[1,0]
	v_mul_f32_e32 v47, v47, v49
	v_pk_mul_f32 v[42:43], v[42:43], v[48:49] op_sel_hi:[1,0]
	v_mul_f32_e32 v49, 0xbfb8aa3b, v40
	v_exp_f32_e32 v49, v49
	s_nop 0
	v_add_f32_e32 v49, 1.0, v49
	v_rcp_f32_e32 v49, v49
	s_nop 0
	v_mul_f32_e32 v49, v40, v49
	v_mul_f32_e32 v40, 0xbfb8aa3b, v41
	v_exp_f32_e32 v40, v40
	v_pk_mul_f32 v[36:37], v[36:37], v[48:49] op_sel_hi:[1,0]
	v_pk_mul_f32 v[38:39], v[38:39], v[48:49] op_sel_hi:[1,0]
	v_pk_mul_f32 v[32:33], v[32:33], v[48:49] op_sel_hi:[1,0]
	v_add_f32_e32 v40, 1.0, v40
	v_rcp_f32_e32 v40, v40
	v_pk_mul_f32 v[34:35], v[34:35], v[48:49] op_sel_hi:[1,0]
	v_mul_f32_e32 v52, v41, v40
	v_mul_f32_e32 v40, 0xbfb8aa3b, v42
	v_exp_f32_e32 v40, v40
	s_nop 0
	v_add_f32_e32 v40, 1.0, v40
	v_rcp_f32_e32 v40, v40
	s_nop 0
	v_mul_f32_e32 v53, v42, v40
	v_mul_f32_e32 v40, 0xbfb8aa3b, v43
	v_exp_f32_e32 v40, v40
	s_nop 0
	v_add_f32_e32 v40, 1.0, v40
	v_rcp_f32_e32 v40, v40
	s_nop 0
	v_mul_f32_e32 v43, v43, v40
	v_cvt_pk_bf16_f32 v40, v44, v45
	v_lshl_add_u64 v[44:45], s[22:23], 0, v[50:51]
	v_lshl_add_u64 v[44:45], v[44:45], 0, v[124:125]
	v_cvt_pk_bf16_f32 v41, v46, v47
	v_cvt_pk_bf16_f32 v42, v49, v52
	v_cvt_pk_bf16_f32 v43, v53, v43
	global_store_dwordx4 v[44:45], v[40:43], off
	s_nop 1
	v_mul_f32_e32 v40, 0xbfb8aa3b, v36
	v_exp_f32_e32 v40, v40
	s_nop 0
	v_add_f32_e32 v40, 1.0, v40
	v_rcp_f32_e32 v40, v40
	s_nop 0
	v_mul_f32_e32 v36, v36, v40
	v_mul_f32_e32 v40, 0xbfb8aa3b, v37
	v_exp_f32_e32 v40, v40
	s_nop 0
	v_add_f32_e32 v40, 1.0, v40
	v_rcp_f32_e32 v40, v40
	s_nop 0
	v_mul_f32_e32 v37, v37, v40
	v_mul_f32_e32 v40, 0xbfb8aa3b, v38
	v_exp_f32_e32 v40, v40
	s_nop 0
	v_add_f32_e32 v40, 1.0, v40
	v_rcp_f32_e32 v40, v40
	s_nop 0
	v_mul_f32_e32 v38, v38, v40
	v_mul_f32_e32 v40, 0xbfb8aa3b, v39
	v_exp_f32_e32 v40, v40
	s_nop 0
	v_add_f32_e32 v40, 1.0, v40
	v_rcp_f32_e32 v40, v40
	s_nop 0
	v_mul_f32_e32 v39, v39, v40
	v_mul_f32_e32 v40, 0xbfb8aa3b, v32
	v_exp_f32_e32 v40, v40
	s_nop 0
	v_add_f32_e32 v40, 1.0, v40
	v_rcp_f32_e32 v40, v40
	s_nop 0
	v_mul_f32_e32 v40, v32, v40
	v_mul_f32_e32 v32, 0xbfb8aa3b, v33
	v_exp_f32_e32 v32, v32
	s_nop 0
	v_add_f32_e32 v32, 1.0, v32
	v_rcp_f32_e32 v32, v32
	s_nop 0
	v_mul_f32_e32 v41, v33, v32
	v_mul_f32_e32 v32, 0xbfb8aa3b, v34
	v_exp_f32_e32 v32, v32
	s_nop 0
	v_add_f32_e32 v32, 1.0, v32
	v_rcp_f32_e32 v32, v32
	s_nop 0
	v_mul_f32_e32 v42, v34, v32
	v_mul_f32_e32 v32, 0xbfb8aa3b, v35
	v_exp_f32_e32 v32, v32
	s_nop 0
	v_add_f32_e32 v32, 1.0, v32
	v_rcp_f32_e32 v32, v32
	s_nop 0
	v_mul_f32_e32 v35, v35, v32
	v_cvt_pk_bf16_f32 v32, v36, v37
	v_cvt_pk_bf16_f32 v33, v38, v39
	v_cvt_pk_bf16_f32 v34, v40, v41
	v_cvt_pk_bf16_f32 v35, v42, v35
	global_store_dwordx4 v[44:45], v[32:35], off offset:256
	s_nop 1
	v_add_u32_e32 v34, 0xa0, v144
	v_ashrrev_i32_e32 v35, 31, v34
	v_lshl_add_u64 v[32:33], v[34:35], 2, s[24:25]
	s_nop 0
	v_lshlrev_b64 v[34:35], 12, v[34:35]
	s_nop 0
	v_fmamk_f32 v32, v246, 0x3a000000, v197
	v_cmp_gt_f32_e32 vcc, s36, v32
	v_mul_f32_e32 v33, 0x4f800000, v32
	s_nop 0
	v_cndmask_b32_e32 v32, v32, v33, vcc
	v_sqrt_f32_e32 v33, v32
	s_nop 0
	v_add_u32_e32 v36, -1, v33
	v_fma_f32 v37, -v36, v33, v32
	v_cmp_ge_f32_e64 s[10:11], 0, v37
	v_add_u32_e32 v37, 1, v33
	s_nop 0
	v_cndmask_b32_e64 v36, v33, v36, s[10:11]
	v_fma_f32 v33, -v37, v33, v32
	v_cmp_lt_f32_e64 s[10:11], 0, v33
	s_nop 1
	v_cndmask_b32_e64 v33, v36, v37, s[10:11]
	v_mul_f32_e32 v36, 0x37800000, v33
	v_cndmask_b32_e32 v33, v33, v36, vcc
	v_cmp_class_f32_e32 vcc, v32, v198
	s_nop 1
	v_cndmask_b32_e32 v32, v33, v32, vcc
	v_div_scale_f32 v33, s[2:3], v32, v32, 1.0
	v_rcp_f32_e32 v36, v33
	s_nop 0
	v_fma_f32 v37, -v33, v36, 1.0
	v_fmac_f32_e32 v36, v37, v36
	v_div_scale_f32 v37, vcc, 1.0, v32, 1.0
	v_mul_f32_e32 v38, v37, v36
	v_fma_f32 v39, -v33, v38, v37
	v_fmac_f32_e32 v38, v39, v36
	v_fma_f32 v33, -v33, v38, v37
	v_div_fmas_f32 v33, v33, v36, v38
	v_div_fixup_f32 v32, v33, v32, 1.0
	v_pk_mul_f32 v[28:29], v[28:29], v[32:33] op_sel_hi:[1,0]
	v_pk_mul_f32 v[30:31], v[30:31], v[32:33] op_sel_hi:[1,0]
	v_mul_f32_e32 v33, 0xbfb8aa3b, v28
	v_exp_f32_e32 v33, v33
	s_nop 0
	v_add_f32_e32 v33, 1.0, v33
	v_rcp_f32_e32 v33, v33
	s_nop 0
	v_mul_f32_e32 v28, v28, v33
	v_mul_f32_e32 v33, 0xbfb8aa3b, v29
	v_exp_f32_e32 v33, v33
	s_nop 0
	v_add_f32_e32 v33, 1.0, v33
	v_rcp_f32_e32 v33, v33
	s_nop 0
	v_mul_f32_e32 v29, v29, v33
	v_mul_f32_e32 v33, 0xbfb8aa3b, v30
	v_exp_f32_e32 v33, v33
	s_nop 0
	v_add_f32_e32 v33, 1.0, v33
	v_rcp_f32_e32 v33, v33
	s_nop 0
	v_mul_f32_e32 v30, v30, v33
	v_mul_f32_e32 v33, 0xbfb8aa3b, v31
	v_exp_f32_e32 v33, v33
	s_nop 0
	v_add_f32_e32 v33, 1.0, v33
	v_rcp_f32_e32 v33, v33
	s_nop 0
	v_pk_mul_f32 v[24:25], v[24:25], v[32:33] op_sel_hi:[1,0]
	v_mul_f32_e32 v31, v31, v33
	v_pk_mul_f32 v[26:27], v[26:27], v[32:33] op_sel_hi:[1,0]
	v_mul_f32_e32 v33, 0xbfb8aa3b, v24
	v_exp_f32_e32 v33, v33
	s_nop 0
	v_add_f32_e32 v33, 1.0, v33
	v_rcp_f32_e32 v33, v33
	s_nop 0
	v_mul_f32_e32 v33, v24, v33
	v_mul_f32_e32 v24, 0xbfb8aa3b, v25
	v_exp_f32_e32 v24, v24
	v_pk_mul_f32 v[20:21], v[20:21], v[32:33] op_sel_hi:[1,0]
	v_pk_mul_f32 v[22:23], v[22:23], v[32:33] op_sel_hi:[1,0]
	v_pk_mul_f32 v[16:17], v[16:17], v[32:33] op_sel_hi:[1,0]
	v_add_f32_e32 v24, 1.0, v24
	v_rcp_f32_e32 v24, v24
	v_pk_mul_f32 v[18:19], v[18:19], v[32:33] op_sel_hi:[1,0]
	v_mul_f32_e32 v36, v25, v24
	v_mul_f32_e32 v24, 0xbfb8aa3b, v26
	v_exp_f32_e32 v24, v24
	s_nop 0
	v_add_f32_e32 v24, 1.0, v24
	v_rcp_f32_e32 v24, v24
	s_nop 0
	v_mul_f32_e32 v37, v26, v24
	v_mul_f32_e32 v24, 0xbfb8aa3b, v27
	v_exp_f32_e32 v24, v24
	s_nop 0
	v_add_f32_e32 v24, 1.0, v24
	v_rcp_f32_e32 v24, v24
	s_nop 0
	v_mul_f32_e32 v27, v27, v24
	v_cvt_pk_bf16_f32 v24, v28, v29
	v_lshl_add_u64 v[28:29], s[22:23], 0, v[34:35]
	v_lshl_add_u64 v[28:29], v[28:29], 0, v[124:125]
	v_cvt_pk_bf16_f32 v25, v30, v31
	v_cvt_pk_bf16_f32 v26, v33, v36
	v_cvt_pk_bf16_f32 v27, v37, v27
	global_store_dwordx4 v[28:29], v[24:27], off
	s_nop 1
	v_mul_f32_e32 v24, 0xbfb8aa3b, v20
	v_exp_f32_e32 v24, v24
	s_nop 0
	v_add_f32_e32 v24, 1.0, v24
	v_rcp_f32_e32 v24, v24
	s_nop 0
	v_mul_f32_e32 v20, v20, v24
	v_mul_f32_e32 v24, 0xbfb8aa3b, v21
	v_exp_f32_e32 v24, v24
	s_nop 0
	v_add_f32_e32 v24, 1.0, v24
	v_rcp_f32_e32 v24, v24
	s_nop 0
	v_mul_f32_e32 v21, v21, v24
	v_mul_f32_e32 v24, 0xbfb8aa3b, v22
	v_exp_f32_e32 v24, v24
	s_nop 0
	v_add_f32_e32 v24, 1.0, v24
	v_rcp_f32_e32 v24, v24
	s_nop 0
	v_mul_f32_e32 v22, v22, v24
	v_mul_f32_e32 v24, 0xbfb8aa3b, v23
	v_exp_f32_e32 v24, v24
	s_nop 0
	v_add_f32_e32 v24, 1.0, v24
	v_rcp_f32_e32 v24, v24
	s_nop 0
	v_mul_f32_e32 v23, v23, v24
	v_mul_f32_e32 v24, 0xbfb8aa3b, v16
	v_exp_f32_e32 v24, v24
	s_nop 0
	v_add_f32_e32 v24, 1.0, v24
	v_rcp_f32_e32 v24, v24
	s_nop 0
	v_mul_f32_e32 v24, v16, v24
	v_mul_f32_e32 v16, 0xbfb8aa3b, v17
	v_exp_f32_e32 v16, v16
	s_nop 0
	v_add_f32_e32 v16, 1.0, v16
	v_rcp_f32_e32 v16, v16
	s_nop 0
	v_mul_f32_e32 v25, v17, v16
	v_mul_f32_e32 v16, 0xbfb8aa3b, v18
	v_exp_f32_e32 v16, v16
	s_nop 0
	v_add_f32_e32 v16, 1.0, v16
	v_rcp_f32_e32 v16, v16
	s_nop 0
	v_mul_f32_e32 v26, v18, v16
	v_mul_f32_e32 v16, 0xbfb8aa3b, v19
	v_exp_f32_e32 v16, v16
	s_nop 0
	v_add_f32_e32 v16, 1.0, v16
	v_rcp_f32_e32 v16, v16
	s_nop 0
	v_mul_f32_e32 v19, v19, v16
	v_cvt_pk_bf16_f32 v16, v20, v21
	v_cvt_pk_bf16_f32 v17, v22, v23
	v_cvt_pk_bf16_f32 v18, v24, v25
	v_cvt_pk_bf16_f32 v19, v26, v19
	global_store_dwordx4 v[28:29], v[16:19], off offset:256
	s_nop 1
	v_add_u32_e32 v18, 0xb0, v144
	v_ashrrev_i32_e32 v19, 31, v18
	v_lshl_add_u64 v[16:17], v[18:19], 2, s[24:25]
	s_nop 0
	v_lshlrev_b64 v[18:19], 12, v[18:19]
	s_nop 0
	v_fmamk_f32 v16, v247, 0x3a000000, v197
	v_cmp_gt_f32_e32 vcc, s36, v16
	v_mul_f32_e32 v17, 0x4f800000, v16
	s_nop 0
	v_cndmask_b32_e32 v16, v16, v17, vcc
	v_sqrt_f32_e32 v17, v16
	s_nop 0
	v_add_u32_e32 v20, -1, v17
	v_fma_f32 v21, -v20, v17, v16
	v_cmp_ge_f32_e64 s[10:11], 0, v21
	v_add_u32_e32 v21, 1, v17
	s_nop 0
	v_cndmask_b32_e64 v20, v17, v20, s[10:11]
	v_fma_f32 v17, -v21, v17, v16
	v_cmp_lt_f32_e64 s[10:11], 0, v17
	s_nop 1
	v_cndmask_b32_e64 v17, v20, v21, s[10:11]
	v_mul_f32_e32 v20, 0x37800000, v17
	v_cndmask_b32_e32 v17, v17, v20, vcc
	v_cmp_class_f32_e32 vcc, v16, v198
	s_nop 1
	v_cndmask_b32_e32 v16, v17, v16, vcc
	v_div_scale_f32 v17, s[2:3], v16, v16, 1.0
	v_rcp_f32_e32 v20, v17
	s_nop 0
	v_fma_f32 v21, -v17, v20, 1.0
	v_fmac_f32_e32 v20, v21, v20
	v_div_scale_f32 v21, vcc, 1.0, v16, 1.0
	v_mul_f32_e32 v22, v21, v20
	v_fma_f32 v23, -v17, v22, v21
	v_fmac_f32_e32 v22, v23, v20
	v_fma_f32 v17, -v17, v22, v21
	v_div_fmas_f32 v17, v17, v20, v22
	v_div_fixup_f32 v16, v17, v16, 1.0
	v_pk_mul_f32 v[12:13], v[12:13], v[16:17] op_sel_hi:[1,0]
	v_pk_mul_f32 v[14:15], v[14:15], v[16:17] op_sel_hi:[1,0]
	v_mul_f32_e32 v17, 0xbfb8aa3b, v12
	v_exp_f32_e32 v17, v17
	s_nop 0
	v_add_f32_e32 v17, 1.0, v17
	v_rcp_f32_e32 v17, v17
	s_nop 0
	v_mul_f32_e32 v12, v12, v17
	v_mul_f32_e32 v17, 0xbfb8aa3b, v13
	v_exp_f32_e32 v17, v17
	s_nop 0
	v_add_f32_e32 v17, 1.0, v17
	v_rcp_f32_e32 v17, v17
	s_nop 0
	v_mul_f32_e32 v13, v13, v17
	v_mul_f32_e32 v17, 0xbfb8aa3b, v14
	v_exp_f32_e32 v17, v17
	s_nop 0
	v_add_f32_e32 v17, 1.0, v17
	v_rcp_f32_e32 v17, v17
	s_nop 0
	v_mul_f32_e32 v14, v14, v17
	v_mul_f32_e32 v17, 0xbfb8aa3b, v15
	v_exp_f32_e32 v17, v17
	s_nop 0
	v_add_f32_e32 v17, 1.0, v17
	v_rcp_f32_e32 v17, v17
	s_nop 0
	v_pk_mul_f32 v[8:9], v[8:9], v[16:17] op_sel_hi:[1,0]
	v_mul_f32_e32 v15, v15, v17
	v_pk_mul_f32 v[10:11], v[10:11], v[16:17] op_sel_hi:[1,0]
	v_mul_f32_e32 v17, 0xbfb8aa3b, v8
	v_exp_f32_e32 v17, v17
	s_nop 0
	v_add_f32_e32 v17, 1.0, v17
	v_rcp_f32_e32 v17, v17
	s_nop 0
	v_mul_f32_e32 v17, v8, v17
	v_mul_f32_e32 v8, 0xbfb8aa3b, v9
	v_exp_f32_e32 v8, v8
	v_pk_mul_f32 v[4:5], v[4:5], v[16:17] op_sel_hi:[1,0]
	v_pk_mul_f32 v[6:7], v[6:7], v[16:17] op_sel_hi:[1,0]
	v_pk_mul_f32 v[0:1], v[0:1], v[16:17] op_sel_hi:[1,0]
	v_add_f32_e32 v8, 1.0, v8
	v_rcp_f32_e32 v8, v8
	v_pk_mul_f32 v[2:3], v[2:3], v[16:17] op_sel_hi:[1,0]
	v_mul_f32_e32 v20, v9, v8
	v_mul_f32_e32 v8, 0xbfb8aa3b, v10
	v_exp_f32_e32 v8, v8
	s_nop 0
	v_add_f32_e32 v8, 1.0, v8
	v_rcp_f32_e32 v8, v8
	s_nop 0
	v_mul_f32_e32 v21, v10, v8
	v_mul_f32_e32 v8, 0xbfb8aa3b, v11
	v_exp_f32_e32 v8, v8
	s_nop 0
	v_add_f32_e32 v8, 1.0, v8
	v_rcp_f32_e32 v8, v8
	s_nop 0
	v_mul_f32_e32 v11, v11, v8
	v_cvt_pk_bf16_f32 v8, v12, v13
	v_lshl_add_u64 v[12:13], s[22:23], 0, v[18:19]
	v_lshl_add_u64 v[12:13], v[12:13], 0, v[124:125]
	v_cvt_pk_bf16_f32 v9, v14, v15
	v_cvt_pk_bf16_f32 v10, v17, v20
	v_cvt_pk_bf16_f32 v11, v21, v11
	global_store_dwordx4 v[12:13], v[8:11], off
	s_nop 1
	v_mul_f32_e32 v8, 0xbfb8aa3b, v4
	v_exp_f32_e32 v8, v8
	s_nop 0
	v_add_f32_e32 v8, 1.0, v8
	v_rcp_f32_e32 v8, v8
	s_nop 0
	v_mul_f32_e32 v4, v4, v8
	v_mul_f32_e32 v8, 0xbfb8aa3b, v5
	v_exp_f32_e32 v8, v8
	s_nop 0
	v_add_f32_e32 v8, 1.0, v8
	v_rcp_f32_e32 v8, v8
	s_nop 0
	v_mul_f32_e32 v5, v5, v8
	v_mul_f32_e32 v8, 0xbfb8aa3b, v6
	v_exp_f32_e32 v8, v8
	s_nop 0
	v_add_f32_e32 v8, 1.0, v8
	v_rcp_f32_e32 v8, v8
	s_nop 0
	v_mul_f32_e32 v6, v6, v8
	v_mul_f32_e32 v8, 0xbfb8aa3b, v7
	v_exp_f32_e32 v8, v8
	s_nop 0
	v_add_f32_e32 v8, 1.0, v8
	v_rcp_f32_e32 v8, v8
	s_nop 0
	v_mul_f32_e32 v7, v7, v8
	v_mul_f32_e32 v8, 0xbfb8aa3b, v0
	v_exp_f32_e32 v8, v8
	s_nop 0
	v_add_f32_e32 v8, 1.0, v8
	v_rcp_f32_e32 v8, v8
	s_nop 0
	v_mul_f32_e32 v8, v0, v8
	v_mul_f32_e32 v0, 0xbfb8aa3b, v1
	v_exp_f32_e32 v0, v0
	s_nop 0
	v_add_f32_e32 v0, 1.0, v0
	v_rcp_f32_e32 v0, v0
	s_nop 0
	v_mul_f32_e32 v9, v1, v0
	v_mul_f32_e32 v0, 0xbfb8aa3b, v2
	v_exp_f32_e32 v0, v0
	s_nop 0
	v_add_f32_e32 v0, 1.0, v0
	v_rcp_f32_e32 v0, v0
	s_nop 0
	v_mul_f32_e32 v10, v2, v0
	v_mul_f32_e32 v0, 0xbfb8aa3b, v3
	v_exp_f32_e32 v0, v0
	s_nop 0
	v_add_f32_e32 v0, 1.0, v0
	v_rcp_f32_e32 v0, v0
	s_nop 0
	v_mul_f32_e32 v3, v3, v0
	v_cvt_pk_bf16_f32 v0, v4, v5
	v_cvt_pk_bf16_f32 v1, v6, v7
	v_cvt_pk_bf16_f32 v2, v8, v9
	v_cvt_pk_bf16_f32 v3, v10, v3
	global_store_dwordx4 v[12:13], v[0:3], off offset:256
	s_andn2_b64 vcc, exec, s[8:9]
	s_mov_b64 s[8:9], -1
	s_cbranch_vccnz .LBB0_496
	s_branch .LBB0_545

.LBB0_509:
	s_or_b64 exec, exec, s[10:11]
	v_or_b32_e32 v152, 16, v146
	v_ashrrev_i32_e32 v153, 31, v152
	v_lshl_add_u64 v[150:151], v[152:153], 2, s[24:25]
	s_nop 0
	v_lshlrev_b64 v[152:153], 10, v[152:153]
	v_lshl_add_u64 v[152:153], v[144:145], 0, v[152:153]
	s_nop 0
	v_fmamk_f32 v147, v241, 0x3a000000, v197
	v_cmp_gt_f32_e32 vcc, s36, v147
	v_mul_f32_e32 v150, 0x4f800000, v147
	s_nop 0
	v_cndmask_b32_e32 v147, v147, v150, vcc
	v_sqrt_f32_e32 v150, v147
	s_nop 0
	v_add_u32_e32 v151, -1, v150
	v_fma_f32 v159, -v151, v150, v147
	v_cmp_ge_f32_e64 s[10:11], 0, v159
	v_add_u32_e32 v159, 1, v150
	s_nop 0
	v_cndmask_b32_e64 v151, v150, v151, s[10:11]
	v_fma_f32 v150, -v159, v150, v147
	v_cmp_lt_f32_e64 s[10:11], 0, v150
	s_nop 1
	v_cndmask_b32_e64 v150, v151, v159, s[10:11]
	v_mul_f32_e32 v151, 0x37800000, v150
	v_cndmask_b32_e32 v150, v150, v151, vcc
	v_cmp_class_f32_e32 vcc, v147, v198
	s_nop 1
	v_cndmask_b32_e32 v147, v150, v147, vcc
	v_div_scale_f32 v150, s[10:11], v147, v147, 1.0
	v_rcp_f32_e32 v151, v150
	s_nop 0
	v_fma_f32 v159, -v150, v151, 1.0
	v_fmac_f32_e32 v151, v159, v151
	v_div_scale_f32 v159, vcc, 1.0, v147, 1.0
	v_mul_f32_e32 v160, v159, v151
	v_fma_f32 v161, -v150, v160, v159
	v_fmac_f32_e32 v160, v161, v151
	v_fma_f32 v150, -v150, v160, v159
	v_div_fmas_f32 v150, v150, v151, v160
	v_div_fixup_f32 v150, v150, v147, 1.0
	v_pk_mul_f32 v[162:163], v[110:111], v[150:151] op_sel_hi:[1,0]
	v_pk_mul_f32 v[160:161], v[108:109], v[150:151] op_sel_hi:[1,0]
	v_pk_mul_f32 v[164:165], v[106:107], v[150:151] op_sel_hi:[1,0]
	v_pk_mul_f32 v[166:167], v[104:105], v[150:151] op_sel_hi:[1,0]
	v_mul_f32_e32 v147, v161, v161
	v_mul_f32_e32 v151, v163, v163
	v_fmac_f32_e32 v147, v160, v160
	v_fmac_f32_e32 v151, v162, v162
	v_add_f32_e32 v147, v147, v151
	v_mul_f32_e32 v151, v167, v167
	v_fmac_f32_e32 v151, v166, v166
	v_add_f32_e32 v147, v151, v147
	v_mul_f32_e32 v151, v165, v165
	v_fmac_f32_e32 v151, v164, v164
	v_cvt_pk_bf16_f32 v160, v160, v161
	v_cvt_pk_bf16_f32 v161, v162, v163
	v_cvt_pk_bf16_f32 v162, v166, v167
	v_cvt_pk_bf16_f32 v163, v164, v165
	global_store_dwordx4 v[152:153], v[160:163], off
	v_add_f32_e32 v147, v151, v147
	v_pk_mul_f32 v[164:165], v[98:99], v[150:151] op_sel_hi:[1,0]
	v_pk_mul_f32 v[162:163], v[102:103], v[150:151] op_sel_hi:[1,0]
	v_pk_mul_f32 v[160:161], v[100:101], v[150:151] op_sel_hi:[1,0]
	v_mul_f32_e32 v166, v163, v163
	v_mul_f32_e32 v159, v161, v161
	v_pk_mul_f32 v[150:151], v[96:97], v[150:151] op_sel_hi:[1,0]
	v_fmac_f32_e32 v159, v160, v160
	v_fmac_f32_e32 v166, v162, v162
	v_add_f32_e32 v159, v159, v166
	v_mul_f32_e32 v166, v151, v151
	v_fmac_f32_e32 v166, v150, v150
	v_add_f32_e32 v159, v166, v159
	v_mul_f32_e32 v166, v165, v165
	v_fmac_f32_e32 v166, v164, v164
	v_add_f32_e32 v159, v166, v159
	v_add_f32_e32 v147, v147, v159
	v_cvt_pk_bf16_f32 v160, v160, v161
	v_cvt_pk_bf16_f32 v161, v162, v163
	v_cvt_pk_bf16_f32 v162, v150, v151
	v_mov_b32_e32 v150, v147
	s_nop 1
	v_permlane16_swap_b32_e32 v147, v150
	v_add_f32_e32 v147, v147, v150
	v_mov_b32_e32 v150, v147
	s_nop 1
	v_permlane32_swap_b32_e32 v147, v150
	v_cvt_pk_bf16_f32 v163, v164, v165
	global_store_dwordx4 v[152:153], v[160:163], off offset:256
	s_and_saveexec_b64 s[10:11], s[6:7]
	s_cbranch_execz .LBB0_511
	v_add_f32_e32 v147, v147, v150
	global_atomic_add_f32 v[148:149], v147, off offset:64
.LBB0_511:
	s_or_b64 exec, exec, s[10:11]
	v_or_b32_e32 v152, 32, v146
	v_ashrrev_i32_e32 v153, 31, v152
	v_lshl_add_u64 v[150:151], v[152:153], 2, s[24:25]
	s_nop 0
	v_lshlrev_b64 v[152:153], 10, v[152:153]
	v_lshl_add_u64 v[152:153], v[144:145], 0, v[152:153]
	s_nop 0
	v_fmamk_f32 v147, v242, 0x3a000000, v197
	v_cmp_gt_f32_e32 vcc, s36, v147
	v_mul_f32_e32 v150, 0x4f800000, v147
	s_nop 0
	v_cndmask_b32_e32 v147, v147, v150, vcc
	v_sqrt_f32_e32 v150, v147
	s_nop 0
	v_add_u32_e32 v151, -1, v150
	v_fma_f32 v159, -v151, v150, v147
	v_cmp_ge_f32_e64 s[10:11], 0, v159
	v_add_u32_e32 v159, 1, v150
	s_nop 0
	v_cndmask_b32_e64 v151, v150, v151, s[10:11]
	v_fma_f32 v150, -v159, v150, v147
	v_cmp_lt_f32_e64 s[10:11], 0, v150
	s_nop 1
	v_cndmask_b32_e64 v150, v151, v159, s[10:11]
	v_mul_f32_e32 v151, 0x37800000, v150
	v_cndmask_b32_e32 v150, v150, v151, vcc
	v_cmp_class_f32_e32 vcc, v147, v198
	s_nop 1
	v_cndmask_b32_e32 v147, v150, v147, vcc
	v_div_scale_f32 v150, s[10:11], v147, v147, 1.0
	v_rcp_f32_e32 v151, v150
	s_nop 0
	v_fma_f32 v159, -v150, v151, 1.0
	v_fmac_f32_e32 v151, v159, v151
	v_div_scale_f32 v159, vcc, 1.0, v147, 1.0
	v_mul_f32_e32 v160, v159, v151
	v_fma_f32 v161, -v150, v160, v159
	v_fmac_f32_e32 v160, v161, v151
	v_fma_f32 v150, -v150, v160, v159
	v_div_fmas_f32 v150, v150, v151, v160
	v_div_fixup_f32 v150, v150, v147, 1.0
	v_pk_mul_f32 v[162:163], v[94:95], v[150:151] op_sel_hi:[1,0]
	v_pk_mul_f32 v[160:161], v[92:93], v[150:151] op_sel_hi:[1,0]
	v_pk_mul_f32 v[164:165], v[90:91], v[150:151] op_sel_hi:[1,0]
	v_pk_mul_f32 v[166:167], v[88:89], v[150:151] op_sel_hi:[1,0]
	v_mul_f32_e32 v147, v161, v161
	v_mul_f32_e32 v151, v163, v163
	v_fmac_f32_e32 v147, v160, v160
	v_fmac_f32_e32 v151, v162, v162
	v_add_f32_e32 v147, v147, v151
	v_mul_f32_e32 v151, v167, v167
	v_fmac_f32_e32 v151, v166, v166
	v_add_f32_e32 v147, v151, v147
	v_mul_f32_e32 v151, v165, v165
	v_fmac_f32_e32 v151, v164, v164
	v_cvt_pk_bf16_f32 v160, v160, v161
	v_cvt_pk_bf16_f32 v161, v162, v163
	v_cvt_pk_bf16_f32 v162, v166, v167
	v_cvt_pk_bf16_f32 v163, v164, v165
	global_store_dwordx4 v[152:153], v[160:163], off
	v_add_f32_e32 v147, v151, v147
	v_pk_mul_f32 v[164:165], v[82:83], v[150:151] op_sel_hi:[1,0]
	v_pk_mul_f32 v[162:163], v[86:87], v[150:151] op_sel_hi:[1,0]
	v_pk_mul_f32 v[160:161], v[84:85], v[150:151] op_sel_hi:[1,0]
	v_mul_f32_e32 v166, v163, v163
	v_mul_f32_e32 v159, v161, v161
	v_pk_mul_f32 v[150:151], v[80:81], v[150:151] op_sel_hi:[1,0]
	v_fmac_f32_e32 v159, v160, v160
	v_fmac_f32_e32 v166, v162, v162
	v_add_f32_e32 v159, v159, v166
	v_mul_f32_e32 v166, v151, v151
	v_fmac_f32_e32 v166, v150, v150
	v_add_f32_e32 v159, v166, v159
	v_mul_f32_e32 v166, v165, v165
	v_fmac_f32_e32 v166, v164, v164
	v_add_f32_e32 v159, v166, v159
	v_add_f32_e32 v147, v147, v159
	v_cvt_pk_bf16_f32 v160, v160, v161
	v_cvt_pk_bf16_f32 v161, v162, v163
	v_cvt_pk_bf16_f32 v162, v150, v151
	v_mov_b32_e32 v150, v147
	s_nop 1
	v_permlane16_swap_b32_e32 v147, v150
	v_add_f32_e32 v147, v147, v150
	v_mov_b32_e32 v150, v147
	s_nop 1
	v_permlane32_swap_b32_e32 v147, v150
	v_cvt_pk_bf16_f32 v163, v164, v165
	global_store_dwordx4 v[152:153], v[160:163], off offset:256
	s_and_saveexec_b64 s[10:11], s[6:7]
	s_cbranch_execz .LBB0_513
	v_add_f32_e32 v147, v147, v150
	global_atomic_add_f32 v[148:149], v147, off offset:128
.LBB0_513:
	s_or_b64 exec, exec, s[10:11]
	v_or_b32_e32 v152, 48, v146
	v_ashrrev_i32_e32 v153, 31, v152
	v_lshl_add_u64 v[150:151], v[152:153], 2, s[24:25]
	s_nop 0
	v_lshlrev_b64 v[152:153], 10, v[152:153]
	v_lshl_add_u64 v[152:153], v[144:145], 0, v[152:153]
	s_nop 0
	v_fmamk_f32 v147, v243, 0x3a000000, v197
	v_cmp_gt_f32_e32 vcc, s36, v147
	v_mul_f32_e32 v150, 0x4f800000, v147
	s_nop 0
	v_cndmask_b32_e32 v147, v147, v150, vcc
	v_sqrt_f32_e32 v150, v147
	s_nop 0
	v_add_u32_e32 v151, -1, v150
	v_fma_f32 v159, -v151, v150, v147
	v_cmp_ge_f32_e64 s[10:11], 0, v159
	v_add_u32_e32 v159, 1, v150
	s_nop 0
	v_cndmask_b32_e64 v151, v150, v151, s[10:11]
	v_fma_f32 v150, -v159, v150, v147
	v_cmp_lt_f32_e64 s[10:11], 0, v150
	s_nop 1
	v_cndmask_b32_e64 v150, v151, v159, s[10:11]
	v_mul_f32_e32 v151, 0x37800000, v150
	v_cndmask_b32_e32 v150, v150, v151, vcc
	v_cmp_class_f32_e32 vcc, v147, v198
	s_nop 1
	v_cndmask_b32_e32 v147, v150, v147, vcc
	v_div_scale_f32 v150, s[10:11], v147, v147, 1.0
	v_rcp_f32_e32 v151, v150
	s_nop 0
	v_fma_f32 v159, -v150, v151, 1.0
	v_fmac_f32_e32 v151, v159, v151
	v_div_scale_f32 v159, vcc, 1.0, v147, 1.0
	v_mul_f32_e32 v160, v159, v151
	v_fma_f32 v161, -v150, v160, v159
	v_fmac_f32_e32 v160, v161, v151
	v_fma_f32 v150, -v150, v160, v159
	v_div_fmas_f32 v150, v150, v151, v160
	v_div_fixup_f32 v150, v150, v147, 1.0
	v_pk_mul_f32 v[162:163], v[78:79], v[150:151] op_sel_hi:[1,0]
	v_pk_mul_f32 v[160:161], v[76:77], v[150:151] op_sel_hi:[1,0]
	v_pk_mul_f32 v[164:165], v[74:75], v[150:151] op_sel_hi:[1,0]
	v_pk_mul_f32 v[166:167], v[72:73], v[150:151] op_sel_hi:[1,0]
	v_mul_f32_e32 v147, v161, v161
	v_mul_f32_e32 v151, v163, v163
	v_fmac_f32_e32 v147, v160, v160
	v_fmac_f32_e32 v151, v162, v162
	v_add_f32_e32 v147, v147, v151
	v_mul_f32_e32 v151, v167, v167
	v_fmac_f32_e32 v151, v166, v166
	v_add_f32_e32 v147, v151, v147
	v_mul_f32_e32 v151, v165, v165
	v_fmac_f32_e32 v151, v164, v164
	v_cvt_pk_bf16_f32 v160, v160, v161
	v_cvt_pk_bf16_f32 v161, v162, v163
	v_cvt_pk_bf16_f32 v162, v166, v167
	v_cvt_pk_bf16_f32 v163, v164, v165
	global_store_dwordx4 v[152:153], v[160:163], off
	v_add_f32_e32 v147, v151, v147
	v_pk_mul_f32 v[164:165], v[66:67], v[150:151] op_sel_hi:[1,0]
	v_pk_mul_f32 v[162:163], v[70:71], v[150:151] op_sel_hi:[1,0]
	v_pk_mul_f32 v[160:161], v[68:69], v[150:151] op_sel_hi:[1,0]
	v_mul_f32_e32 v166, v163, v163
	v_mul_f32_e32 v159, v161, v161
	v_pk_mul_f32 v[150:151], v[64:65], v[150:151] op_sel_hi:[1,0]
	v_fmac_f32_e32 v159, v160, v160
	v_fmac_f32_e32 v166, v162, v162
	v_add_f32_e32 v159, v159, v166
	v_mul_f32_e32 v166, v151, v151
	v_fmac_f32_e32 v166, v150, v150
	v_add_f32_e32 v159, v166, v159
	v_mul_f32_e32 v166, v165, v165
	v_fmac_f32_e32 v166, v164, v164
	v_add_f32_e32 v159, v166, v159
	v_add_f32_e32 v147, v147, v159
	v_cvt_pk_bf16_f32 v160, v160, v161
	v_cvt_pk_bf16_f32 v161, v162, v163
	v_cvt_pk_bf16_f32 v162, v150, v151
	v_mov_b32_e32 v150, v147
	s_nop 1
	v_permlane16_swap_b32_e32 v147, v150
	v_add_f32_e32 v147, v147, v150
	v_mov_b32_e32 v150, v147
	s_nop 1
	v_permlane32_swap_b32_e32 v147, v150
	v_cvt_pk_bf16_f32 v163, v164, v165
	global_store_dwordx4 v[152:153], v[160:163], off offset:256
	s_and_saveexec_b64 s[10:11], s[6:7]
	s_cbranch_execz .LBB0_515
	v_add_f32_e32 v147, v147, v150
	global_atomic_add_f32 v[148:149], v147, off offset:192
.LBB0_515:
	s_or_b64 exec, exec, s[10:11]
	v_add_u32_e32 v152, 0x80, v146
	v_ashrrev_i32_e32 v153, 31, v152
	v_lshl_add_u64 v[150:151], v[152:153], 2, s[24:25]
	s_nop 0
	v_lshlrev_b64 v[152:153], 10, v[152:153]
	v_lshl_add_u64 v[152:153], v[144:145], 0, v[152:153]
	s_nop 0
	v_fmamk_f32 v147, v244, 0x3a000000, v197
	v_cmp_gt_f32_e32 vcc, s36, v147
	v_mul_f32_e32 v150, 0x4f800000, v147
	s_nop 0
	v_cndmask_b32_e32 v147, v147, v150, vcc
	v_sqrt_f32_e32 v150, v147
	s_nop 0
	v_add_u32_e32 v151, -1, v150
	v_fma_f32 v159, -v151, v150, v147
	v_cmp_ge_f32_e64 s[10:11], 0, v159
	v_add_u32_e32 v159, 1, v150
	s_nop 0
	v_cndmask_b32_e64 v151, v150, v151, s[10:11]
	v_fma_f32 v150, -v159, v150, v147
	v_cmp_lt_f32_e64 s[10:11], 0, v150
	s_nop 1
	v_cndmask_b32_e64 v150, v151, v159, s[10:11]
	v_mul_f32_e32 v151, 0x37800000, v150
	v_cndmask_b32_e32 v150, v150, v151, vcc
	v_cmp_class_f32_e32 vcc, v147, v198
	s_nop 1
	v_cndmask_b32_e32 v147, v150, v147, vcc
	v_div_scale_f32 v150, s[10:11], v147, v147, 1.0
	v_rcp_f32_e32 v151, v150
	s_nop 0
	v_fma_f32 v159, -v150, v151, 1.0
	v_fmac_f32_e32 v151, v159, v151
	v_div_scale_f32 v159, vcc, 1.0, v147, 1.0
	v_mul_f32_e32 v160, v159, v151
	v_fma_f32 v161, -v150, v160, v159
	v_fmac_f32_e32 v160, v161, v151
	v_fma_f32 v150, -v150, v160, v159
	v_div_fmas_f32 v150, v150, v151, v160
	v_div_fixup_f32 v150, v150, v147, 1.0
	v_pk_mul_f32 v[162:163], v[62:63], v[150:151] op_sel_hi:[1,0]
	v_pk_mul_f32 v[160:161], v[60:61], v[150:151] op_sel_hi:[1,0]
	v_pk_mul_f32 v[164:165], v[58:59], v[150:151] op_sel_hi:[1,0]
	v_pk_mul_f32 v[166:167], v[56:57], v[150:151] op_sel_hi:[1,0]
	v_mul_f32_e32 v147, v161, v161
	v_mul_f32_e32 v151, v163, v163
	v_fmac_f32_e32 v147, v160, v160
	v_fmac_f32_e32 v151, v162, v162
	v_add_f32_e32 v147, v147, v151
	v_mul_f32_e32 v151, v167, v167
	v_fmac_f32_e32 v151, v166, v166
	v_add_f32_e32 v147, v151, v147
	v_mul_f32_e32 v151, v165, v165
	v_fmac_f32_e32 v151, v164, v164
	v_cvt_pk_bf16_f32 v160, v160, v161
	v_cvt_pk_bf16_f32 v161, v162, v163
	v_cvt_pk_bf16_f32 v162, v166, v167
	v_cvt_pk_bf16_f32 v163, v164, v165
	global_store_dwordx4 v[152:153], v[160:163], off
	v_add_f32_e32 v147, v151, v147
	v_pk_mul_f32 v[164:165], v[50:51], v[150:151] op_sel_hi:[1,0]
	v_pk_mul_f32 v[162:163], v[54:55], v[150:151] op_sel_hi:[1,0]
	v_pk_mul_f32 v[160:161], v[52:53], v[150:151] op_sel_hi:[1,0]
	v_mul_f32_e32 v166, v163, v163
	v_mul_f32_e32 v159, v161, v161
	v_pk_mul_f32 v[150:151], v[48:49], v[150:151] op_sel_hi:[1,0]
	v_fmac_f32_e32 v159, v160, v160
	v_fmac_f32_e32 v166, v162, v162
	v_add_f32_e32 v159, v159, v166
	v_mul_f32_e32 v166, v151, v151
	v_fmac_f32_e32 v166, v150, v150
	v_add_f32_e32 v159, v166, v159
	v_mul_f32_e32 v166, v165, v165
	v_fmac_f32_e32 v166, v164, v164
	v_add_f32_e32 v159, v166, v159
	v_add_f32_e32 v147, v147, v159
	v_cvt_pk_bf16_f32 v160, v160, v161
	v_cvt_pk_bf16_f32 v161, v162, v163
	v_cvt_pk_bf16_f32 v162, v150, v151
	v_mov_b32_e32 v150, v147
	s_nop 1
	v_permlane16_swap_b32_e32 v147, v150
	v_add_f32_e32 v147, v147, v150
	v_mov_b32_e32 v150, v147
	s_nop 1
	v_permlane32_swap_b32_e32 v147, v150
	v_cvt_pk_bf16_f32 v163, v164, v165
	global_store_dwordx4 v[152:153], v[160:163], off offset:256
	s_and_saveexec_b64 s[10:11], s[6:7]
	s_cbranch_execz .LBB0_517
	v_add_f32_e32 v147, v147, v150
	global_atomic_add_f32 v[148:149], v147, off offset:512
.LBB0_517:
	s_or_b64 exec, exec, s[10:11]
	v_add_u32_e32 v152, 0x90, v146
	v_ashrrev_i32_e32 v153, 31, v152
	v_lshl_add_u64 v[150:151], v[152:153], 2, s[24:25]
	s_nop 0
	v_lshlrev_b64 v[152:153], 10, v[152:153]
	v_lshl_add_u64 v[152:153], v[144:145], 0, v[152:153]
	s_nop 0
	v_fmamk_f32 v147, v245, 0x3a000000, v197
	v_cmp_gt_f32_e32 vcc, s36, v147
	v_mul_f32_e32 v150, 0x4f800000, v147
	s_nop 0
	v_cndmask_b32_e32 v147, v147, v150, vcc
	v_sqrt_f32_e32 v150, v147
	s_nop 0
	v_add_u32_e32 v151, -1, v150
	v_fma_f32 v159, -v151, v150, v147
	v_cmp_ge_f32_e64 s[10:11], 0, v159
	v_add_u32_e32 v159, 1, v150
	s_nop 0
	v_cndmask_b32_e64 v151, v150, v151, s[10:11]
	v_fma_f32 v150, -v159, v150, v147
	v_cmp_lt_f32_e64 s[10:11], 0, v150
	s_nop 1
	v_cndmask_b32_e64 v150, v151, v159, s[10:11]
	v_mul_f32_e32 v151, 0x37800000, v150
	v_cndmask_b32_e32 v150, v150, v151, vcc
	v_cmp_class_f32_e32 vcc, v147, v198
	s_nop 1
	v_cndmask_b32_e32 v147, v150, v147, vcc
	v_div_scale_f32 v150, s[10:11], v147, v147, 1.0
	v_rcp_f32_e32 v151, v150
	s_nop 0
	v_fma_f32 v159, -v150, v151, 1.0
	v_fmac_f32_e32 v151, v159, v151
	v_div_scale_f32 v159, vcc, 1.0, v147, 1.0
	v_mul_f32_e32 v160, v159, v151
	v_fma_f32 v161, -v150, v160, v159
	v_fmac_f32_e32 v160, v161, v151
	v_fma_f32 v150, -v150, v160, v159
	v_div_fmas_f32 v150, v150, v151, v160
	v_div_fixup_f32 v150, v150, v147, 1.0
	v_pk_mul_f32 v[162:163], v[46:47], v[150:151] op_sel_hi:[1,0]
	v_pk_mul_f32 v[160:161], v[44:45], v[150:151] op_sel_hi:[1,0]
	v_pk_mul_f32 v[164:165], v[42:43], v[150:151] op_sel_hi:[1,0]
	v_pk_mul_f32 v[166:167], v[40:41], v[150:151] op_sel_hi:[1,0]
	v_mul_f32_e32 v147, v161, v161
	v_mul_f32_e32 v151, v163, v163
	v_fmac_f32_e32 v147, v160, v160
	v_fmac_f32_e32 v151, v162, v162
	v_add_f32_e32 v147, v147, v151
	v_mul_f32_e32 v151, v167, v167
	v_fmac_f32_e32 v151, v166, v166
	v_add_f32_e32 v147, v151, v147
	v_mul_f32_e32 v151, v165, v165
	v_fmac_f32_e32 v151, v164, v164
	v_cvt_pk_bf16_f32 v160, v160, v161
	v_cvt_pk_bf16_f32 v161, v162, v163
	v_cvt_pk_bf16_f32 v162, v166, v167
	v_cvt_pk_bf16_f32 v163, v164, v165
	global_store_dwordx4 v[152:153], v[160:163], off
	v_add_f32_e32 v147, v151, v147
	v_pk_mul_f32 v[164:165], v[34:35], v[150:151] op_sel_hi:[1,0]
	v_pk_mul_f32 v[162:163], v[38:39], v[150:151] op_sel_hi:[1,0]
	v_pk_mul_f32 v[160:161], v[36:37], v[150:151] op_sel_hi:[1,0]
	v_mul_f32_e32 v166, v163, v163
	v_mul_f32_e32 v159, v161, v161
	v_pk_mul_f32 v[150:151], v[32:33], v[150:151] op_sel_hi:[1,0]
	v_fmac_f32_e32 v159, v160, v160
	v_fmac_f32_e32 v166, v162, v162
	v_add_f32_e32 v159, v159, v166
	v_mul_f32_e32 v166, v151, v151
	v_fmac_f32_e32 v166, v150, v150
	v_add_f32_e32 v159, v166, v159
	v_mul_f32_e32 v166, v165, v165
	v_fmac_f32_e32 v166, v164, v164
	v_add_f32_e32 v159, v166, v159
	v_add_f32_e32 v147, v147, v159
	v_cvt_pk_bf16_f32 v160, v160, v161
	v_cvt_pk_bf16_f32 v161, v162, v163
	v_cvt_pk_bf16_f32 v162, v150, v151
	v_mov_b32_e32 v150, v147
	s_nop 1
	v_permlane16_swap_b32_e32 v147, v150
	v_add_f32_e32 v147, v147, v150
	v_mov_b32_e32 v150, v147
	s_nop 1
	v_permlane32_swap_b32_e32 v147, v150
	v_cvt_pk_bf16_f32 v163, v164, v165
	global_store_dwordx4 v[152:153], v[160:163], off offset:256
	s_and_saveexec_b64 s[10:11], s[6:7]
	s_cbranch_execz .LBB0_519
	v_add_f32_e32 v147, v147, v150
	global_atomic_add_f32 v[148:149], v147, off offset:576
.LBB0_519:
	s_or_b64 exec, exec, s[10:11]
	v_add_u32_e32 v152, 0xa0, v146
	v_ashrrev_i32_e32 v153, 31, v152
	v_lshl_add_u64 v[150:151], v[152:153], 2, s[24:25]
	s_nop 0
	v_lshlrev_b64 v[152:153], 10, v[152:153]
	v_lshl_add_u64 v[152:153], v[144:145], 0, v[152:153]
	s_nop 0
	v_fmamk_f32 v147, v246, 0x3a000000, v197
	v_cmp_gt_f32_e32 vcc, s36, v147
	v_mul_f32_e32 v150, 0x4f800000, v147
	s_nop 0
	v_cndmask_b32_e32 v147, v147, v150, vcc
	v_sqrt_f32_e32 v150, v147
	s_nop 0
	v_add_u32_e32 v151, -1, v150
	v_fma_f32 v159, -v151, v150, v147
	v_cmp_ge_f32_e64 s[10:11], 0, v159
	v_add_u32_e32 v159, 1, v150
	s_nop 0
	v_cndmask_b32_e64 v151, v150, v151, s[10:11]
	v_fma_f32 v150, -v159, v150, v147
	v_cmp_lt_f32_e64 s[10:11], 0, v150
	s_nop 1
	v_cndmask_b32_e64 v150, v151, v159, s[10:11]
	v_mul_f32_e32 v151, 0x37800000, v150
	v_cndmask_b32_e32 v150, v150, v151, vcc
	v_cmp_class_f32_e32 vcc, v147, v198
	s_nop 1
	v_cndmask_b32_e32 v147, v150, v147, vcc
	v_div_scale_f32 v150, s[10:11], v147, v147, 1.0
	v_rcp_f32_e32 v151, v150
	s_nop 0
	v_fma_f32 v159, -v150, v151, 1.0
	v_fmac_f32_e32 v151, v159, v151
	v_div_scale_f32 v159, vcc, 1.0, v147, 1.0
	v_mul_f32_e32 v160, v159, v151
	v_fma_f32 v161, -v150, v160, v159
	v_fmac_f32_e32 v160, v161, v151
	v_fma_f32 v150, -v150, v160, v159
	v_div_fmas_f32 v150, v150, v151, v160
	v_div_fixup_f32 v150, v150, v147, 1.0
	v_pk_mul_f32 v[162:163], v[30:31], v[150:151] op_sel_hi:[1,0]
	v_pk_mul_f32 v[160:161], v[28:29], v[150:151] op_sel_hi:[1,0]
	v_pk_mul_f32 v[164:165], v[26:27], v[150:151] op_sel_hi:[1,0]
	v_pk_mul_f32 v[166:167], v[24:25], v[150:151] op_sel_hi:[1,0]
	v_mul_f32_e32 v147, v161, v161
	v_mul_f32_e32 v151, v163, v163
	v_fmac_f32_e32 v147, v160, v160
	v_fmac_f32_e32 v151, v162, v162
	v_add_f32_e32 v147, v147, v151
	v_mul_f32_e32 v151, v167, v167
	v_fmac_f32_e32 v151, v166, v166
	v_add_f32_e32 v147, v151, v147
	v_mul_f32_e32 v151, v165, v165
	v_fmac_f32_e32 v151, v164, v164
	v_cvt_pk_bf16_f32 v160, v160, v161
	v_cvt_pk_bf16_f32 v161, v162, v163
	v_cvt_pk_bf16_f32 v162, v166, v167
	v_cvt_pk_bf16_f32 v163, v164, v165
	global_store_dwordx4 v[152:153], v[160:163], off
	v_add_f32_e32 v147, v151, v147
	v_pk_mul_f32 v[164:165], v[18:19], v[150:151] op_sel_hi:[1,0]
	v_pk_mul_f32 v[162:163], v[22:23], v[150:151] op_sel_hi:[1,0]
	v_pk_mul_f32 v[160:161], v[20:21], v[150:151] op_sel_hi:[1,0]
	v_mul_f32_e32 v166, v163, v163
	v_mul_f32_e32 v159, v161, v161
	v_pk_mul_f32 v[150:151], v[16:17], v[150:151] op_sel_hi:[1,0]
	v_fmac_f32_e32 v159, v160, v160
	v_fmac_f32_e32 v166, v162, v162
	v_add_f32_e32 v159, v159, v166
	v_mul_f32_e32 v166, v151, v151
	v_fmac_f32_e32 v166, v150, v150
	v_add_f32_e32 v159, v166, v159
	v_mul_f32_e32 v166, v165, v165
	v_fmac_f32_e32 v166, v164, v164
	v_add_f32_e32 v159, v166, v159
	v_add_f32_e32 v147, v147, v159
	v_cvt_pk_bf16_f32 v160, v160, v161
	v_cvt_pk_bf16_f32 v161, v162, v163
	v_cvt_pk_bf16_f32 v162, v150, v151
	v_mov_b32_e32 v150, v147
	s_nop 1
	v_permlane16_swap_b32_e32 v147, v150
	v_add_f32_e32 v147, v147, v150
	v_mov_b32_e32 v150, v147
	s_nop 1
	v_permlane32_swap_b32_e32 v147, v150
	v_cvt_pk_bf16_f32 v163, v164, v165
	global_store_dwordx4 v[152:153], v[160:163], off offset:256
	s_and_saveexec_b64 s[10:11], s[6:7]
	s_cbranch_execz .LBB0_521
	v_add_f32_e32 v147, v147, v150
	global_atomic_add_f32 v[148:149], v147, off offset:640
.LBB0_521:
	s_or_b64 exec, exec, s[10:11]
	v_add_u32_e32 v150, 0xb0, v146
	v_ashrrev_i32_e32 v151, 31, v150
	v_lshl_add_u64 v[146:147], v[150:151], 2, s[24:25]
	s_nop 0
	v_lshlrev_b64 v[150:151], 10, v[150:151]
	v_lshl_add_u64 v[144:145], v[144:145], 0, v[150:151]
	s_nop 0
	v_fmamk_f32 v146, v247, 0x3a000000, v197
	v_cmp_gt_f32_e32 vcc, s36, v146
	v_mul_f32_e32 v147, 0x4f800000, v146
	s_nop 0
	v_cndmask_b32_e32 v146, v146, v147, vcc
	v_sqrt_f32_e32 v147, v146
	s_nop 0
	v_add_u32_e32 v152, -1, v147
	v_fma_f32 v153, -v152, v147, v146
	v_cmp_ge_f32_e64 s[10:11], 0, v153
	v_add_u32_e32 v153, 1, v147
	s_nop 0
	v_cndmask_b32_e64 v152, v147, v152, s[10:11]
	v_fma_f32 v147, -v153, v147, v146
	v_cmp_lt_f32_e64 s[10:11], 0, v147
	s_nop 1
	v_cndmask_b32_e64 v147, v152, v153, s[10:11]
	v_mul_f32_e32 v152, 0x37800000, v147
	v_cndmask_b32_e32 v147, v147, v152, vcc
	v_cmp_class_f32_e32 vcc, v146, v198
	s_nop 1
	v_cndmask_b32_e32 v146, v147, v146, vcc
	v_div_scale_f32 v147, s[10:11], v146, v146, 1.0
	v_rcp_f32_e32 v152, v147
	s_nop 0
	v_fma_f32 v153, -v147, v152, 1.0
	v_fmac_f32_e32 v152, v153, v152
	v_div_scale_f32 v153, vcc, 1.0, v146, 1.0
	v_mul_f32_e32 v159, v153, v152
	v_fma_f32 v160, -v147, v159, v153
	v_fmac_f32_e32 v159, v160, v152
	v_fma_f32 v147, -v147, v159, v153
	v_div_fmas_f32 v147, v147, v152, v159
	v_div_fixup_f32 v146, v147, v146, 1.0
	v_pk_mul_f32 v[152:153], v[14:15], v[146:147] op_sel_hi:[1,0]
	v_pk_mul_f32 v[150:151], v[12:13], v[146:147] op_sel_hi:[1,0]
	v_pk_mul_f32 v[160:161], v[10:11], v[146:147] op_sel_hi:[1,0]
	v_pk_mul_f32 v[162:163], v[8:9], v[146:147] op_sel_hi:[1,0]
	v_mul_f32_e32 v147, v151, v151
	v_mul_f32_e32 v159, v153, v153
	v_fmac_f32_e32 v147, v150, v150
	v_fmac_f32_e32 v159, v152, v152
	v_add_f32_e32 v147, v147, v159
	v_mul_f32_e32 v159, v163, v163
	v_fmac_f32_e32 v159, v162, v162
	v_add_f32_e32 v147, v159, v147
	v_cvt_pk_bf16_f32 v150, v150, v151
	v_cvt_pk_bf16_f32 v151, v152, v153
	v_cvt_pk_bf16_f32 v152, v162, v163
	v_cvt_pk_bf16_f32 v153, v160, v161
	v_mul_f32_e32 v159, v161, v161
	global_store_dwordx4 v[144:145], v[150:153], off
	v_fmac_f32_e32 v159, v160, v160
	v_add_f32_e32 v159, v159, v147
	v_pk_mul_f32 v[152:153], v[6:7], v[146:147] op_sel_hi:[1,0]
	v_pk_mul_f32 v[150:151], v[4:5], v[146:147] op_sel_hi:[1,0]
	v_mul_f32_e32 v163, v153, v153
	v_mul_f32_e32 v162, v151, v151
	v_pk_mul_f32 v[160:161], v[2:3], v[146:147] op_sel_hi:[1,0]
	v_pk_mul_f32 v[146:147], v[0:1], v[146:147] op_sel_hi:[1,0]
	v_fmac_f32_e32 v162, v150, v150
	v_fmac_f32_e32 v163, v152, v152
	v_add_f32_e32 v162, v162, v163
	v_mul_f32_e32 v163, v147, v147
	v_fmac_f32_e32 v163, v146, v146
	v_add_f32_e32 v162, v163, v162
	v_mul_f32_e32 v163, v161, v161
	v_fmac_f32_e32 v163, v160, v160
	v_add_f32_e32 v162, v163, v162
	v_add_f32_e32 v159, v159, v162
	v_cvt_pk_bf16_f32 v150, v150, v151
	v_cvt_pk_bf16_f32 v151, v152, v153
	v_cvt_pk_bf16_f32 v152, v146, v147
	v_cvt_pk_bf16_f32 v153, v160, v161
	global_store_dwordx4 v[144:145], v[150:153], off offset:256
	v_mov_b32_e32 v144, v159
	s_nop 1
	v_permlane16_swap_b32_e32 v159, v144
	v_add_f32_e32 v144, v159, v144
	v_mov_b32_e32 v145, v144
	s_nop 1
	v_permlane32_swap_b32_e32 v144, v145
	s_and_saveexec_b64 s[10:11], s[6:7]
	s_cbranch_execz .LBB0_523
	v_add_f32_e32 v144, v144, v145
	global_atomic_add_f32 v[148:149], v144, off offset:704

.LBB0_528:
	s_or_b64 exec, exec, s[10:11]
	v_or_b32_e32 v146, 16, v144
	v_ashrrev_i32_e32 v147, 31, v146
	v_lshl_add_u64 v[148:149], v[146:147], 2, s[24:25]
	s_nop 0
	s_nop 0
	v_fmamk_f32 v145, v241, 0x3a000000, v197
	v_mul_f32_e32 v148, 0x4f800000, v145
	v_cmp_gt_f32_e32 vcc, s36, v145
	s_nop 1
	v_cndmask_b32_e32 v145, v145, v148, vcc
	v_sqrt_f32_e32 v150, v145
	v_lshlrev_b64 v[148:149], 8, v[146:147]
	v_add_u32_e32 v151, -1, v150
	v_add_u32_e32 v152, 1, v150
	v_fma_f32 v153, -v151, v150, v145
	v_fma_f32 v159, -v152, v150, v145
	v_cmp_ge_f32_e64 s[10:11], 0, v153
	s_nop 1
	v_cndmask_b32_e64 v150, v150, v151, s[10:11]
	v_cmp_lt_f32_e64 s[10:11], 0, v159
	s_nop 1
	v_cndmask_b32_e64 v150, v150, v152, s[10:11]
	v_mul_f32_e32 v151, 0x37800000, v150
	v_cndmask_b32_e32 v150, v150, v151, vcc
	v_cmp_class_f32_e32 vcc, v145, v198
	v_lshl_add_u64 v[152:153], v[136:137], 0, v[148:149]
	s_nop 0
	v_cndmask_b32_e32 v145, v150, v145, vcc
	v_div_scale_f32 v150, s[10:11], v145, v145, 1.0
	v_rcp_f32_e32 v151, v150
	v_div_scale_f32 v148, vcc, 1.0, v145, 1.0
	v_fma_f32 v149, -v150, v151, 1.0
	v_fmac_f32_e32 v151, v149, v151
	v_mul_f32_e32 v149, v148, v151
	v_fma_f32 v159, -v150, v149, v148
	v_fmac_f32_e32 v149, v159, v151
	v_fma_f32 v148, -v150, v149, v148
	v_div_fmas_f32 v148, v148, v151, v149
	v_div_fixup_f32 v160, v148, v145, 1.0
	v_pk_mul_f32 v[150:151], v[110:111], v[160:161] op_sel_hi:[1,0]
	v_pk_mul_f32 v[148:149], v[108:109], v[160:161] op_sel_hi:[1,0]
	v_pk_mul_f32 v[162:163], v[106:107], v[160:161] op_sel_hi:[1,0]
	v_pk_mul_f32 v[160:161], v[104:105], v[160:161] op_sel_hi:[1,0]
	global_store_dwordx4 v[152:153], v[148:151], off
	global_store_dwordx4 v[152:153], v[160:163], off offset:16
	v_mul_f32_e32 v145, v149, v149
	v_mul_f32_e32 v149, v151, v151
	v_mul_f32_e32 v151, v161, v161
	v_fmac_f32_e32 v145, v148, v148
	v_fmac_f32_e32 v149, v150, v150
	v_mul_f32_e32 v152, v163, v163
	v_fmac_f32_e32 v151, v160, v160
	v_add_f32_e32 v145, v145, v149
	v_fmac_f32_e32 v152, v162, v162
	v_add_f32_e32 v145, v151, v145
	v_add_f32_e32 v145, v152, v145
	v_mov_b32_e32 v148, v145
	s_nop 1
	v_permlane16_swap_b32_e32 v145, v148
	v_add_f32_e32 v145, v145, v148
	v_mov_b32_e32 v148, v145
	s_nop 1
	v_permlane32_swap_b32_e32 v145, v148
	s_and_saveexec_b64 s[10:11], s[6:7]
	s_cbranch_execz .LBB0_530
	v_lshl_add_u64 v[146:147], v[146:147], 2, s[26:27]
	v_add_f32_e32 v145, v145, v148
	global_atomic_add_f32 v[146:147], v145, off
.LBB0_530:
	s_or_b64 exec, exec, s[10:11]
	v_or_b32_e32 v146, 32, v144
	v_ashrrev_i32_e32 v147, 31, v146
	v_lshl_add_u64 v[148:149], v[146:147], 2, s[24:25]
	s_nop 0
	s_nop 0
	v_fmamk_f32 v145, v242, 0x3a000000, v197
	v_mul_f32_e32 v148, 0x4f800000, v145
	v_cmp_gt_f32_e32 vcc, s36, v145
	s_nop 1
	v_cndmask_b32_e32 v145, v145, v148, vcc
	v_sqrt_f32_e32 v150, v145
	v_lshlrev_b64 v[148:149], 8, v[146:147]
	v_add_u32_e32 v151, -1, v150
	v_add_u32_e32 v152, 1, v150
	v_fma_f32 v153, -v151, v150, v145
	v_fma_f32 v159, -v152, v150, v145
	v_cmp_ge_f32_e64 s[10:11], 0, v153
	s_nop 1
	v_cndmask_b32_e64 v150, v150, v151, s[10:11]
	v_cmp_lt_f32_e64 s[10:11], 0, v159
	s_nop 1
	v_cndmask_b32_e64 v150, v150, v152, s[10:11]
	v_mul_f32_e32 v151, 0x37800000, v150
	v_cndmask_b32_e32 v150, v150, v151, vcc
	v_cmp_class_f32_e32 vcc, v145, v198
	v_lshl_add_u64 v[152:153], v[136:137], 0, v[148:149]
	s_nop 0
	v_cndmask_b32_e32 v145, v150, v145, vcc
	v_div_scale_f32 v150, s[10:11], v145, v145, 1.0
	v_rcp_f32_e32 v151, v150
	v_div_scale_f32 v148, vcc, 1.0, v145, 1.0
	v_fma_f32 v149, -v150, v151, 1.0
	v_fmac_f32_e32 v151, v149, v151
	v_mul_f32_e32 v149, v148, v151
	v_fma_f32 v159, -v150, v149, v148
	v_fmac_f32_e32 v149, v159, v151
	v_fma_f32 v148, -v150, v149, v148
	v_div_fmas_f32 v148, v148, v151, v149
	v_div_fixup_f32 v160, v148, v145, 1.0
	v_pk_mul_f32 v[150:151], v[94:95], v[160:161] op_sel_hi:[1,0]
	v_pk_mul_f32 v[148:149], v[92:93], v[160:161] op_sel_hi:[1,0]
	v_pk_mul_f32 v[162:163], v[90:91], v[160:161] op_sel_hi:[1,0]
	v_pk_mul_f32 v[160:161], v[88:89], v[160:161] op_sel_hi:[1,0]
	global_store_dwordx4 v[152:153], v[148:151], off
	global_store_dwordx4 v[152:153], v[160:163], off offset:16
	v_mul_f32_e32 v145, v149, v149
	v_mul_f32_e32 v149, v151, v151
	v_mul_f32_e32 v151, v161, v161
	v_fmac_f32_e32 v145, v148, v148
	v_fmac_f32_e32 v149, v150, v150
	v_mul_f32_e32 v152, v163, v163
	v_fmac_f32_e32 v151, v160, v160
	v_add_f32_e32 v145, v145, v149
	v_fmac_f32_e32 v152, v162, v162
	v_add_f32_e32 v145, v151, v145
	v_add_f32_e32 v145, v152, v145
	v_mov_b32_e32 v148, v145
	s_nop 1
	v_permlane16_swap_b32_e32 v145, v148
	v_add_f32_e32 v145, v145, v148
	v_mov_b32_e32 v148, v145
	s_nop 1
	v_permlane32_swap_b32_e32 v145, v148
	s_and_saveexec_b64 s[10:11], s[6:7]
	s_cbranch_execz .LBB0_532
	v_lshl_add_u64 v[146:147], v[146:147], 2, s[26:27]
	v_add_f32_e32 v145, v145, v148
	global_atomic_add_f32 v[146:147], v145, off
.LBB0_532:
	s_or_b64 exec, exec, s[10:11]
	v_or_b32_e32 v146, 48, v144
	v_ashrrev_i32_e32 v147, 31, v146
	v_lshl_add_u64 v[148:149], v[146:147], 2, s[24:25]
	s_nop 0
	s_nop 0
	v_fmamk_f32 v145, v243, 0x3a000000, v197
	v_mul_f32_e32 v148, 0x4f800000, v145
	v_cmp_gt_f32_e32 vcc, s36, v145
	s_nop 1
	v_cndmask_b32_e32 v145, v145, v148, vcc
	v_sqrt_f32_e32 v150, v145
	v_lshlrev_b64 v[148:149], 8, v[146:147]
	v_add_u32_e32 v151, -1, v150
	v_add_u32_e32 v152, 1, v150
	v_fma_f32 v153, -v151, v150, v145
	v_fma_f32 v159, -v152, v150, v145
	v_cmp_ge_f32_e64 s[10:11], 0, v153
	s_nop 1
	v_cndmask_b32_e64 v150, v150, v151, s[10:11]
	v_cmp_lt_f32_e64 s[10:11], 0, v159
	s_nop 1
	v_cndmask_b32_e64 v150, v150, v152, s[10:11]
	v_mul_f32_e32 v151, 0x37800000, v150
	v_cndmask_b32_e32 v150, v150, v151, vcc
	v_cmp_class_f32_e32 vcc, v145, v198
	v_lshl_add_u64 v[152:153], v[136:137], 0, v[148:149]
	s_nop 0
	v_cndmask_b32_e32 v145, v150, v145, vcc
	v_div_scale_f32 v150, s[10:11], v145, v145, 1.0
	v_rcp_f32_e32 v151, v150
	v_div_scale_f32 v148, vcc, 1.0, v145, 1.0
	v_fma_f32 v149, -v150, v151, 1.0
	v_fmac_f32_e32 v151, v149, v151
	v_mul_f32_e32 v149, v148, v151
	v_fma_f32 v159, -v150, v149, v148
	v_fmac_f32_e32 v149, v159, v151
	v_fma_f32 v148, -v150, v149, v148
	v_div_fmas_f32 v148, v148, v151, v149
	v_div_fixup_f32 v160, v148, v145, 1.0
	v_pk_mul_f32 v[150:151], v[78:79], v[160:161] op_sel_hi:[1,0]
	v_pk_mul_f32 v[148:149], v[76:77], v[160:161] op_sel_hi:[1,0]
	v_pk_mul_f32 v[162:163], v[74:75], v[160:161] op_sel_hi:[1,0]
	v_pk_mul_f32 v[160:161], v[72:73], v[160:161] op_sel_hi:[1,0]
	global_store_dwordx4 v[152:153], v[148:151], off
	global_store_dwordx4 v[152:153], v[160:163], off offset:16
	v_mul_f32_e32 v145, v149, v149
	v_mul_f32_e32 v149, v151, v151
	v_mul_f32_e32 v151, v161, v161
	v_fmac_f32_e32 v145, v148, v148
	v_fmac_f32_e32 v149, v150, v150
	v_mul_f32_e32 v152, v163, v163
	v_fmac_f32_e32 v151, v160, v160
	v_add_f32_e32 v145, v145, v149
	v_fmac_f32_e32 v152, v162, v162
	v_add_f32_e32 v145, v151, v145
	v_add_f32_e32 v145, v152, v145
	v_mov_b32_e32 v148, v145
	s_nop 1
	v_permlane16_swap_b32_e32 v145, v148
	v_add_f32_e32 v145, v145, v148
	v_mov_b32_e32 v148, v145
	s_nop 1
	v_permlane32_swap_b32_e32 v145, v148
	s_and_saveexec_b64 s[10:11], s[6:7]
	s_cbranch_execz .LBB0_534
	v_lshl_add_u64 v[146:147], v[146:147], 2, s[26:27]
	v_add_f32_e32 v145, v145, v148
	global_atomic_add_f32 v[146:147], v145, off
.LBB0_534:
	s_or_b64 exec, exec, s[10:11]
	v_add_u32_e32 v146, 0x80, v144
	v_ashrrev_i32_e32 v147, 31, v146
	v_lshl_add_u64 v[148:149], v[146:147], 2, s[24:25]
	s_nop 0
	s_nop 0
	v_fmamk_f32 v145, v244, 0x3a000000, v197
	v_mul_f32_e32 v148, 0x4f800000, v145
	v_cmp_gt_f32_e32 vcc, s36, v145
	s_nop 1
	v_cndmask_b32_e32 v145, v145, v148, vcc
	v_sqrt_f32_e32 v150, v145
	v_lshlrev_b64 v[148:149], 8, v[146:147]
	v_add_u32_e32 v151, -1, v150
	v_add_u32_e32 v152, 1, v150
	v_fma_f32 v153, -v151, v150, v145
	v_fma_f32 v159, -v152, v150, v145
	v_cmp_ge_f32_e64 s[10:11], 0, v153
	s_nop 1
	v_cndmask_b32_e64 v150, v150, v151, s[10:11]
	v_cmp_lt_f32_e64 s[10:11], 0, v159
	s_nop 1
	v_cndmask_b32_e64 v150, v150, v152, s[10:11]
	v_mul_f32_e32 v151, 0x37800000, v150
	v_cndmask_b32_e32 v150, v150, v151, vcc
	v_cmp_class_f32_e32 vcc, v145, v198
	v_lshl_add_u64 v[152:153], v[136:137], 0, v[148:149]
	s_nop 0
	v_cndmask_b32_e32 v145, v150, v145, vcc
	v_div_scale_f32 v150, s[10:11], v145, v145, 1.0
	v_rcp_f32_e32 v151, v150
	v_div_scale_f32 v148, vcc, 1.0, v145, 1.0
	v_fma_f32 v149, -v150, v151, 1.0
	v_fmac_f32_e32 v151, v149, v151
	v_mul_f32_e32 v149, v148, v151
	v_fma_f32 v159, -v150, v149, v148
	v_fmac_f32_e32 v149, v159, v151
	v_fma_f32 v148, -v150, v149, v148
	v_div_fmas_f32 v148, v148, v151, v149
	v_div_fixup_f32 v160, v148, v145, 1.0
	v_pk_mul_f32 v[150:151], v[62:63], v[160:161] op_sel_hi:[1,0]
	v_pk_mul_f32 v[148:149], v[60:61], v[160:161] op_sel_hi:[1,0]
	v_pk_mul_f32 v[162:163], v[58:59], v[160:161] op_sel_hi:[1,0]
	v_pk_mul_f32 v[160:161], v[56:57], v[160:161] op_sel_hi:[1,0]
	global_store_dwordx4 v[152:153], v[148:151], off
	global_store_dwordx4 v[152:153], v[160:163], off offset:16
	v_mul_f32_e32 v145, v149, v149
	v_mul_f32_e32 v149, v151, v151
	v_mul_f32_e32 v151, v161, v161
	v_fmac_f32_e32 v145, v148, v148
	v_fmac_f32_e32 v149, v150, v150
	v_mul_f32_e32 v152, v163, v163
	v_fmac_f32_e32 v151, v160, v160
	v_add_f32_e32 v145, v145, v149
	v_fmac_f32_e32 v152, v162, v162
	v_add_f32_e32 v145, v151, v145
	v_add_f32_e32 v145, v152, v145
	v_mov_b32_e32 v148, v145
	s_nop 1
	v_permlane16_swap_b32_e32 v145, v148
	v_add_f32_e32 v145, v145, v148
	v_mov_b32_e32 v148, v145
	s_nop 1
	v_permlane32_swap_b32_e32 v145, v148
	s_and_saveexec_b64 s[10:11], s[6:7]
	s_cbranch_execz .LBB0_536
	v_lshl_add_u64 v[146:147], v[146:147], 2, s[26:27]
	v_add_f32_e32 v145, v145, v148
	global_atomic_add_f32 v[146:147], v145, off
.LBB0_536:
	s_or_b64 exec, exec, s[10:11]
	v_add_u32_e32 v146, 0x90, v144
	v_ashrrev_i32_e32 v147, 31, v146
	v_lshl_add_u64 v[148:149], v[146:147], 2, s[24:25]
	s_nop 0
	s_nop 0
	v_fmamk_f32 v145, v245, 0x3a000000, v197
	v_mul_f32_e32 v148, 0x4f800000, v145
	v_cmp_gt_f32_e32 vcc, s36, v145
	s_nop 1
	v_cndmask_b32_e32 v145, v145, v148, vcc
	v_sqrt_f32_e32 v150, v145
	v_lshlrev_b64 v[148:149], 8, v[146:147]
	v_add_u32_e32 v151, -1, v150
	v_add_u32_e32 v152, 1, v150
	v_fma_f32 v153, -v151, v150, v145
	v_fma_f32 v159, -v152, v150, v145
	v_cmp_ge_f32_e64 s[10:11], 0, v153
	s_nop 1
	v_cndmask_b32_e64 v150, v150, v151, s[10:11]
	v_cmp_lt_f32_e64 s[10:11], 0, v159
	s_nop 1
	v_cndmask_b32_e64 v150, v150, v152, s[10:11]
	v_mul_f32_e32 v151, 0x37800000, v150
	v_cndmask_b32_e32 v150, v150, v151, vcc
	v_cmp_class_f32_e32 vcc, v145, v198
	v_lshl_add_u64 v[152:153], v[136:137], 0, v[148:149]
	s_nop 0
	v_cndmask_b32_e32 v145, v150, v145, vcc
	v_div_scale_f32 v150, s[10:11], v145, v145, 1.0
	v_rcp_f32_e32 v151, v150
	v_div_scale_f32 v148, vcc, 1.0, v145, 1.0
	v_fma_f32 v149, -v150, v151, 1.0
	v_fmac_f32_e32 v151, v149, v151
	v_mul_f32_e32 v149, v148, v151
	v_fma_f32 v159, -v150, v149, v148
	v_fmac_f32_e32 v149, v159, v151
	v_fma_f32 v148, -v150, v149, v148
	v_div_fmas_f32 v148, v148, v151, v149
	v_div_fixup_f32 v160, v148, v145, 1.0
	v_pk_mul_f32 v[150:151], v[46:47], v[160:161] op_sel_hi:[1,0]
	v_pk_mul_f32 v[148:149], v[44:45], v[160:161] op_sel_hi:[1,0]
	v_pk_mul_f32 v[162:163], v[42:43], v[160:161] op_sel_hi:[1,0]
	v_pk_mul_f32 v[160:161], v[40:41], v[160:161] op_sel_hi:[1,0]
	global_store_dwordx4 v[152:153], v[148:151], off
	global_store_dwordx4 v[152:153], v[160:163], off offset:16
	v_mul_f32_e32 v145, v149, v149
	v_mul_f32_e32 v149, v151, v151
	v_mul_f32_e32 v151, v161, v161
	v_fmac_f32_e32 v145, v148, v148
	v_fmac_f32_e32 v149, v150, v150
	v_mul_f32_e32 v152, v163, v163
	v_fmac_f32_e32 v151, v160, v160
	v_add_f32_e32 v145, v145, v149
	v_fmac_f32_e32 v152, v162, v162
	v_add_f32_e32 v145, v151, v145
	v_add_f32_e32 v145, v152, v145
	v_mov_b32_e32 v148, v145
	s_nop 1
	v_permlane16_swap_b32_e32 v145, v148
	v_add_f32_e32 v145, v145, v148
	v_mov_b32_e32 v148, v145
	s_nop 1
	v_permlane32_swap_b32_e32 v145, v148
	s_and_saveexec_b64 s[10:11], s[6:7]
	s_cbranch_execz .LBB0_538
	v_lshl_add_u64 v[146:147], v[146:147], 2, s[26:27]
	v_add_f32_e32 v145, v145, v148
	global_atomic_add_f32 v[146:147], v145, off
.LBB0_538:
	s_or_b64 exec, exec, s[10:11]
	v_add_u32_e32 v146, 0xa0, v144
	v_ashrrev_i32_e32 v147, 31, v146
	v_lshl_add_u64 v[148:149], v[146:147], 2, s[24:25]
	s_nop 0
	s_nop 0
	v_fmamk_f32 v145, v246, 0x3a000000, v197
	v_mul_f32_e32 v148, 0x4f800000, v145
	v_cmp_gt_f32_e32 vcc, s36, v145
	s_nop 1
	v_cndmask_b32_e32 v145, v145, v148, vcc
	v_sqrt_f32_e32 v150, v145
	v_lshlrev_b64 v[148:149], 8, v[146:147]
	v_add_u32_e32 v151, -1, v150
	v_add_u32_e32 v152, 1, v150
	v_fma_f32 v153, -v151, v150, v145
	v_fma_f32 v159, -v152, v150, v145
	v_cmp_ge_f32_e64 s[10:11], 0, v153
	s_nop 1
	v_cndmask_b32_e64 v150, v150, v151, s[10:11]
	v_cmp_lt_f32_e64 s[10:11], 0, v159
	s_nop 1
	v_cndmask_b32_e64 v150, v150, v152, s[10:11]
	v_mul_f32_e32 v151, 0x37800000, v150
	v_cndmask_b32_e32 v150, v150, v151, vcc
	v_cmp_class_f32_e32 vcc, v145, v198
	v_lshl_add_u64 v[152:153], v[136:137], 0, v[148:149]
	s_nop 0
	v_cndmask_b32_e32 v145, v150, v145, vcc
	v_div_scale_f32 v150, s[10:11], v145, v145, 1.0
	v_rcp_f32_e32 v151, v150
	v_div_scale_f32 v148, vcc, 1.0, v145, 1.0
	v_fma_f32 v149, -v150, v151, 1.0
	v_fmac_f32_e32 v151, v149, v151
	v_mul_f32_e32 v149, v148, v151
	v_fma_f32 v159, -v150, v149, v148
	v_fmac_f32_e32 v149, v159, v151
	v_fma_f32 v148, -v150, v149, v148
	v_div_fmas_f32 v148, v148, v151, v149
	v_div_fixup_f32 v160, v148, v145, 1.0
	v_pk_mul_f32 v[150:151], v[30:31], v[160:161] op_sel_hi:[1,0]
	v_pk_mul_f32 v[148:149], v[28:29], v[160:161] op_sel_hi:[1,0]
	v_pk_mul_f32 v[162:163], v[26:27], v[160:161] op_sel_hi:[1,0]
	v_pk_mul_f32 v[160:161], v[24:25], v[160:161] op_sel_hi:[1,0]
	global_store_dwordx4 v[152:153], v[148:151], off
	global_store_dwordx4 v[152:153], v[160:163], off offset:16
	v_mul_f32_e32 v145, v149, v149
	v_mul_f32_e32 v149, v151, v151
	v_mul_f32_e32 v151, v161, v161
	v_fmac_f32_e32 v145, v148, v148
	v_fmac_f32_e32 v149, v150, v150
	v_mul_f32_e32 v152, v163, v163
	v_fmac_f32_e32 v151, v160, v160
	v_add_f32_e32 v145, v145, v149
	v_fmac_f32_e32 v152, v162, v162
	v_add_f32_e32 v145, v151, v145
	v_add_f32_e32 v145, v152, v145
	v_mov_b32_e32 v148, v145
	s_nop 1
	v_permlane16_swap_b32_e32 v145, v148
	v_add_f32_e32 v145, v145, v148
	v_mov_b32_e32 v148, v145
	s_nop 1
	v_permlane32_swap_b32_e32 v145, v148
	s_and_saveexec_b64 s[10:11], s[6:7]
	s_cbranch_execz .LBB0_540
	v_lshl_add_u64 v[146:147], v[146:147], 2, s[26:27]
	v_add_f32_e32 v145, v145, v148
	global_atomic_add_f32 v[146:147], v145, off
.LBB0_540:
	s_or_b64 exec, exec, s[10:11]
	v_add_u32_e32 v144, 0xb0, v144
	v_ashrrev_i32_e32 v145, 31, v144
	v_lshl_add_u64 v[146:147], v[144:145], 2, s[24:25]
	s_nop 0
	s_nop 0
	v_fmamk_f32 v146, v247, 0x3a000000, v197
	v_mul_f32_e32 v147, 0x4f800000, v146
	v_cmp_gt_f32_e32 vcc, s36, v146
	s_nop 1
	v_cndmask_b32_e32 v148, v146, v147, vcc
	v_sqrt_f32_e32 v149, v148
	v_lshlrev_b64 v[146:147], 8, v[144:145]
	v_lshl_add_u64 v[160:161], v[136:137], 0, v[146:147]
	v_add_u32_e32 v150, -1, v149
	v_add_u32_e32 v151, 1, v149
	v_fma_f32 v152, -v150, v149, v148
	v_fma_f32 v153, -v151, v149, v148
	v_cmp_ge_f32_e64 s[10:11], 0, v152
	s_nop 1
	v_cndmask_b32_e64 v149, v149, v150, s[10:11]
	v_cmp_lt_f32_e64 s[10:11], 0, v153
	s_nop 1
	v_cndmask_b32_e64 v149, v149, v151, s[10:11]
	v_mul_f32_e32 v150, 0x37800000, v149
	v_cndmask_b32_e32 v149, v149, v150, vcc
	v_cmp_class_f32_e32 vcc, v148, v198
	s_nop 1
	v_cndmask_b32_e32 v148, v149, v148, vcc
	v_div_scale_f32 v149, s[10:11], v148, v148, 1.0
	v_rcp_f32_e32 v150, v149
	v_div_scale_f32 v146, vcc, 1.0, v148, 1.0
	v_fma_f32 v147, -v149, v150, 1.0
	v_fmac_f32_e32 v150, v147, v150
	v_mul_f32_e32 v147, v146, v150
	v_fma_f32 v151, -v149, v147, v146
	v_fmac_f32_e32 v147, v151, v150
	v_fma_f32 v146, -v149, v147, v146
	v_div_fmas_f32 v146, v146, v150, v147
	v_div_fixup_f32 v150, v146, v148, 1.0
	v_pk_mul_f32 v[148:149], v[14:15], v[150:151] op_sel_hi:[1,0]
	v_pk_mul_f32 v[146:147], v[12:13], v[150:151] op_sel_hi:[1,0]
	v_pk_mul_f32 v[152:153], v[10:11], v[150:151] op_sel_hi:[1,0]
	v_pk_mul_f32 v[150:151], v[8:9], v[150:151] op_sel_hi:[1,0]
	global_store_dwordx4 v[160:161], v[146:149], off
	global_store_dwordx4 v[160:161], v[150:153], off offset:16
	s_nop 0
	v_mul_f32_e32 v147, v147, v147
	v_mul_f32_e32 v149, v149, v149
	v_mul_f32_e32 v151, v151, v151
	v_fmac_f32_e32 v147, v146, v146
	v_fmac_f32_e32 v149, v148, v148
	v_mul_f32_e32 v153, v153, v153
	v_fmac_f32_e32 v151, v150, v150
	v_add_f32_e32 v146, v147, v149
	v_fmac_f32_e32 v153, v152, v152
	v_add_f32_e32 v146, v151, v146
	v_add_f32_e32 v146, v153, v146
	v_mov_b32_e32 v147, v146
	s_nop 1
	v_permlane16_swap_b32_e32 v146, v147
	v_add_f32_e32 v146, v146, v147
	v_mov_b32_e32 v147, v146
	s_nop 1
	v_permlane32_swap_b32_e32 v146, v147
	s_and_saveexec_b64 s[10:11], s[6:7]
	s_cbranch_execz .LBB0_542
	v_lshl_add_u64 v[144:145], v[144:145], 2, s[26:27]
	v_add_f32_e32 v146, v146, v147
	global_atomic_add_f32 v[144:145], v146, off

.LBB0_673:
	s_lshl_b32 s23, s52, 8
	s_add_i32 s23, s23, s49
	v_or_b32_e32 v144, s23, v152
	v_ashrrev_i32_e32 v145, 31, v144
	v_lshl_add_u64 v[150:151], v[144:145], 2, s[18:19]
	global_load_dword v240, v[150:151], off
	global_load_dword v241, v[150:151], off offset:64
	global_load_dword v242, v[150:151], off offset:128
	global_load_dword v243, v[150:151], off offset:192
	v_lshl_or_b32 v140, s4, 8, v154
	v_mul_hi_i32 v141, v140, s69
	v_or_b32_e32 v142, 0x80, v140
	v_lshrrev_b32_e32 v143, 31, v141
	v_ashrrev_i32_e32 v141, 5, v141
	v_mul_hi_i32 v145, v142, s69
	s_ashr_i32 s4, s23, 8
	v_add_u32_e32 v156, v141, v143
	v_lshrrev_b32_e32 v143, 31, v145
	v_ashrrev_i32_e32 v145, 5, v145
	s_and_b32 s4, s4, -16
	v_add_u32_e32 v145, v145, v143
	v_add_u32_e32 v146, s4, v156
	v_add_u32_e32 v148, s4, v145
	v_ashrrev_i32_e32 v147, 31, v146
	v_ashrrev_i32_e32 v149, 31, v148
	v_bitop3_b32 v160, s23, v199, v152 bitop3:0xc8
	v_lshlrev_b64 v[146:147], 12, v[146:147]
	v_lshlrev_b64 v[148:149], 12, v[148:149]
	v_mov_b64_e32 v[138:139], s[16:17]
	v_or_b32_e32 v158, v146, v160
	v_or_b32_e32 v160, v148, v160
	v_mad_u64_u32 v[140:141], s[10:11], v156, s73, v[140:141]
	v_mad_u64_u32 v[142:143], s[10:11], v145, s73, v[142:143]
	v_mad_u64_u32 v[158:159], s[10:11], v158, s35, v[138:139]
	v_ashrrev_i32_e32 v141, 31, v140
	v_ashrrev_i32_e32 v143, 31, v142
	v_lshlrev_b64 v[140:141], 1, v[140:141]
	v_lshlrev_b64 v[142:143], 1, v[142:143]
	v_mad_i32_i24 v159, v147, s35, v159
	v_lshl_add_u64 v[158:159], v[158:159], 0, v[140:141]
	s_addk_i32 s23, 0x80
	s_ashr_i32 s4, s23, 8
	s_and_b32 s4, s4, -16
	s_waitcnt vmcnt(0)
	v_fmamk_f32 v157, v240, 0x3b000000, v197
	v_mul_f32_e32 v161, 0x4f800000, v157
	v_cmp_gt_f32_e32 vcc, s36, v157
	s_nop 1
	v_cndmask_b32_e32 v157, v157, v161, vcc
	v_sqrt_f32_e32 v162, v157
	v_mad_u64_u32 v[160:161], s[10:11], v160, s35, v[138:139]
	v_mad_i32_i24 v161, v149, s35, v161
	v_add_u32_e32 v163, -1, v162
	v_add_u32_e32 v164, 1, v162
	v_fma_f32 v165, -v163, v162, v157
	v_fma_f32 v166, -v164, v162, v157
	v_cmp_ge_f32_e64 s[10:11], 0, v165
	v_lshl_add_u64 v[160:161], v[160:161], 0, v[142:143]
	s_nop 0
	v_cndmask_b32_e64 v162, v162, v163, s[10:11]
	v_cmp_lt_f32_e64 s[10:11], 0, v166
	s_nop 1
	v_cndmask_b32_e64 v162, v162, v164, s[10:11]
	v_mul_f32_e32 v163, 0x37800000, v162
	v_cndmask_b32_e32 v162, v162, v163, vcc
	v_cmp_class_f32_e32 vcc, v157, v198
	s_nop 1
	v_cndmask_b32_e32 v157, v162, v157, vcc
	v_div_scale_f32 v162, s[10:11], v157, v157, 1.0
	v_rcp_f32_e32 v163, v162
	v_div_scale_f32 v164, vcc, 1.0, v157, 1.0
	v_fma_f32 v165, -v162, v163, 1.0
	v_fmac_f32_e32 v163, v165, v163
	v_mul_f32_e32 v165, v164, v163
	v_fma_f32 v166, -v162, v165, v164
	v_fmac_f32_e32 v165, v166, v163
	v_fma_f32 v162, -v162, v165, v164
	v_div_fmas_f32 v162, v162, v163, v165
	v_div_fixup_f32 v162, v162, v157, 1.0
	v_pk_mul_f32 v[126:127], v[126:127], v[162:163] op_sel_hi:[1,0]
	v_pk_mul_f32 v[124:125], v[124:125], v[162:163] op_sel_hi:[1,0]
	v_pk_mul_f32 v[122:123], v[122:123], v[162:163] op_sel_hi:[1,0]
	v_pk_mul_f32 v[120:121], v[120:121], v[162:163] op_sel_hi:[1,0]
	v_pk_mul_f32 v[118:119], v[118:119], v[162:163] op_sel_hi:[1,0]
	v_pk_mul_f32 v[116:117], v[116:117], v[162:163] op_sel_hi:[1,0]
	v_pk_mul_f32 v[164:165], v[114:115], v[162:163] op_sel_hi:[1,0]
	v_pk_mul_f32 v[162:163], v[112:113], v[162:163] op_sel_hi:[1,0]
	v_cvt_pk_bf16_f32 v112, v124, v125
	v_cvt_pk_bf16_f32 v113, v126, v127
	v_cvt_pk_bf16_f32 v114, v120, v121
	v_cvt_pk_bf16_f32 v115, v122, v123
	global_store_dwordx4 v[158:159], v[112:115], off
	s_nop 1
	v_cvt_pk_bf16_f32 v112, v116, v117
	v_cvt_pk_bf16_f32 v113, v118, v119
	v_cvt_pk_bf16_f32 v114, v162, v163
	v_cvt_pk_bf16_f32 v115, v164, v165
	global_store_dwordx4 v[160:161], v[112:115], off
	s_nop 0
	s_nop 0
	v_bitop3_b32 v115, v144, s74, 16 bitop3:0xc8
	v_or_b32_e32 v112, v146, v115
	v_or_b32_e32 v115, v148, v115
	v_mad_u64_u32 v[112:113], s[10:11], v112, s35, v[138:139]
	v_mad_i32_i24 v113, v147, s35, v113
	v_lshl_add_u64 v[112:113], v[112:113], 0, v[140:141]
	s_nop 0
	v_fmamk_f32 v114, v241, 0x3b000000, v197
	v_mul_f32_e32 v116, 0x4f800000, v114
	v_cmp_gt_f32_e32 vcc, s36, v114
	s_nop 1
	v_cndmask_b32_e32 v116, v114, v116, vcc
	v_sqrt_f32_e32 v117, v116
	v_mad_u64_u32 v[114:115], s[10:11], v115, s35, v[138:139]
	v_mad_i32_i24 v115, v149, s35, v115
	v_add_u32_e32 v118, -1, v117
	v_add_u32_e32 v119, 1, v117
	v_fma_f32 v120, -v118, v117, v116
	v_fma_f32 v121, -v119, v117, v116
	v_cmp_ge_f32_e64 s[10:11], 0, v120
	v_lshl_add_u64 v[114:115], v[114:115], 0, v[142:143]
	s_nop 0
	v_cndmask_b32_e64 v117, v117, v118, s[10:11]
	v_cmp_lt_f32_e64 s[10:11], 0, v121
	s_nop 1
	v_cndmask_b32_e64 v117, v117, v119, s[10:11]
	v_mul_f32_e32 v118, 0x37800000, v117
	v_cndmask_b32_e32 v117, v117, v118, vcc
	v_cmp_class_f32_e32 vcc, v116, v198
	s_nop 1
	v_cndmask_b32_e32 v116, v117, v116, vcc
	v_div_scale_f32 v117, s[10:11], v116, v116, 1.0
	v_rcp_f32_e32 v118, v117
	v_div_scale_f32 v119, vcc, 1.0, v116, 1.0
	v_fma_f32 v120, -v117, v118, 1.0
	v_fmac_f32_e32 v118, v120, v118
	v_mul_f32_e32 v120, v119, v118
	v_fma_f32 v121, -v117, v120, v119
	v_fmac_f32_e32 v120, v121, v118
	v_fma_f32 v117, -v117, v120, v119
	v_div_fmas_f32 v117, v117, v118, v120
	v_div_fixup_f32 v116, v117, v116, 1.0
	v_pk_mul_f32 v[110:111], v[110:111], v[116:117] op_sel_hi:[1,0]
	v_pk_mul_f32 v[108:109], v[108:109], v[116:117] op_sel_hi:[1,0]
	v_pk_mul_f32 v[106:107], v[106:107], v[116:117] op_sel_hi:[1,0]
	v_pk_mul_f32 v[104:105], v[104:105], v[116:117] op_sel_hi:[1,0]
	v_pk_mul_f32 v[102:103], v[102:103], v[116:117] op_sel_hi:[1,0]
	v_pk_mul_f32 v[100:101], v[100:101], v[116:117] op_sel_hi:[1,0]
	v_pk_mul_f32 v[118:119], v[98:99], v[116:117] op_sel_hi:[1,0]
	v_pk_mul_f32 v[116:117], v[96:97], v[116:117] op_sel_hi:[1,0]
	v_cvt_pk_bf16_f32 v96, v108, v109
	v_cvt_pk_bf16_f32 v97, v110, v111
	v_cvt_pk_bf16_f32 v98, v104, v105
	v_cvt_pk_bf16_f32 v99, v106, v107
	global_store_dwordx4 v[112:113], v[96:99], off
	s_nop 1
	v_cvt_pk_bf16_f32 v96, v100, v101
	v_cvt_pk_bf16_f32 v97, v102, v103
	v_cvt_pk_bf16_f32 v98, v116, v117
	v_cvt_pk_bf16_f32 v99, v118, v119
	global_store_dwordx4 v[114:115], v[96:99], off
	s_nop 0
	s_nop 0
	v_bitop3_b32 v99, v144, s75, 32 bitop3:0xc8
	v_or_b32_e32 v96, v146, v99
	v_or_b32_e32 v99, v148, v99
	v_mad_u64_u32 v[96:97], s[10:11], v96, s35, v[138:139]
	v_mad_i32_i24 v97, v147, s35, v97
	v_lshl_add_u64 v[96:97], v[96:97], 0, v[140:141]
	s_nop 0
	v_fmamk_f32 v98, v242, 0x3b000000, v197
	v_mul_f32_e32 v100, 0x4f800000, v98
	v_cmp_gt_f32_e32 vcc, s36, v98
	s_nop 1
	v_cndmask_b32_e32 v100, v98, v100, vcc
	v_sqrt_f32_e32 v101, v100
	v_mad_u64_u32 v[98:99], s[10:11], v99, s35, v[138:139]
	v_mad_i32_i24 v99, v149, s35, v99
	v_add_u32_e32 v102, -1, v101
	v_add_u32_e32 v103, 1, v101
	v_fma_f32 v104, -v102, v101, v100
	v_fma_f32 v105, -v103, v101, v100
	v_cmp_ge_f32_e64 s[10:11], 0, v104
	v_lshl_add_u64 v[98:99], v[98:99], 0, v[142:143]
	s_nop 0
	v_cndmask_b32_e64 v101, v101, v102, s[10:11]
	v_cmp_lt_f32_e64 s[10:11], 0, v105
	s_nop 1
	v_cndmask_b32_e64 v101, v101, v103, s[10:11]
	v_mul_f32_e32 v102, 0x37800000, v101
	v_cndmask_b32_e32 v101, v101, v102, vcc
	v_cmp_class_f32_e32 vcc, v100, v198
	s_nop 1
	v_cndmask_b32_e32 v100, v101, v100, vcc
	v_div_scale_f32 v101, s[10:11], v100, v100, 1.0
	v_rcp_f32_e32 v102, v101
	v_div_scale_f32 v103, vcc, 1.0, v100, 1.0
	v_fma_f32 v104, -v101, v102, 1.0
	v_fmac_f32_e32 v102, v104, v102
	v_mul_f32_e32 v104, v103, v102
	v_fma_f32 v105, -v101, v104, v103
	v_fmac_f32_e32 v104, v105, v102
	v_fma_f32 v101, -v101, v104, v103
	v_div_fmas_f32 v101, v101, v102, v104
	v_div_fixup_f32 v100, v101, v100, 1.0
	v_pk_mul_f32 v[94:95], v[94:95], v[100:101] op_sel_hi:[1,0]
	v_pk_mul_f32 v[92:93], v[92:93], v[100:101] op_sel_hi:[1,0]
	v_pk_mul_f32 v[90:91], v[90:91], v[100:101] op_sel_hi:[1,0]
	v_pk_mul_f32 v[88:89], v[88:89], v[100:101] op_sel_hi:[1,0]
	v_pk_mul_f32 v[86:87], v[86:87], v[100:101] op_sel_hi:[1,0]
	v_pk_mul_f32 v[84:85], v[84:85], v[100:101] op_sel_hi:[1,0]
	v_pk_mul_f32 v[102:103], v[82:83], v[100:101] op_sel_hi:[1,0]
	v_pk_mul_f32 v[100:101], v[80:81], v[100:101] op_sel_hi:[1,0]
	v_cvt_pk_bf16_f32 v80, v92, v93
	v_cvt_pk_bf16_f32 v81, v94, v95
	v_cvt_pk_bf16_f32 v82, v88, v89
	v_cvt_pk_bf16_f32 v83, v90, v91
	global_store_dwordx4 v[96:97], v[80:83], off
	s_nop 1
	v_cvt_pk_bf16_f32 v80, v84, v85
	v_cvt_pk_bf16_f32 v81, v86, v87
	v_cvt_pk_bf16_f32 v82, v100, v101
	v_cvt_pk_bf16_f32 v83, v102, v103
	global_store_dwordx4 v[98:99], v[80:83], off
	s_nop 0
	v_bitop3_b32 v87, v144, s77, 48 bitop3:0xc8
	v_or_b32_e32 v80, s23, v152
	v_ashrrev_i32_e32 v81, 31, v80
	v_lshl_add_u64 v[82:83], v[80:81], 2, s[18:19]
	v_or_b32_e32 v81, v146, v87
	v_mad_u64_u32 v[84:85], s[10:11], v81, s35, v[138:139]
	v_or_b32_e32 v81, v148, v87
	v_mad_i32_i24 v85, v147, s35, v85
	v_lshl_add_u64 v[84:85], v[84:85], 0, v[140:141]
	s_nop 0
	v_fmamk_f32 v86, v243, 0x3b000000, v197
	v_mul_f32_e32 v87, 0x4f800000, v86
	v_cmp_gt_f32_e32 vcc, s36, v86
	s_nop 1
	v_cndmask_b32_e32 v88, v86, v87, vcc
	v_sqrt_f32_e32 v89, v88
	v_mad_u64_u32 v[86:87], s[10:11], v81, s35, v[138:139]
	v_mad_i32_i24 v87, v149, s35, v87
	v_add_u32_e32 v81, -1, v89
	v_add_u32_e32 v90, 1, v89
	v_fma_f32 v91, -v81, v89, v88
	v_fma_f32 v92, -v90, v89, v88
	v_cmp_ge_f32_e64 s[10:11], 0, v91
	v_lshl_add_u64 v[86:87], v[86:87], 0, v[142:143]
	s_nop 0
	v_cndmask_b32_e64 v81, v89, v81, s[10:11]
	v_cmp_lt_f32_e64 s[10:11], 0, v92
	s_nop 1
	v_cndmask_b32_e64 v81, v81, v90, s[10:11]
	v_mul_f32_e32 v89, 0x37800000, v81
	v_cndmask_b32_e32 v81, v81, v89, vcc
	v_cmp_class_f32_e32 vcc, v88, v198
	s_nop 1
	v_cndmask_b32_e32 v81, v81, v88, vcc
	v_div_scale_f32 v88, s[10:11], v81, v81, 1.0
	v_rcp_f32_e32 v89, v88
	v_div_scale_f32 v90, vcc, 1.0, v81, 1.0
	v_fma_f32 v91, -v88, v89, 1.0
	v_fmac_f32_e32 v89, v91, v89
	v_mul_f32_e32 v91, v90, v89
	v_fma_f32 v92, -v88, v91, v90
	v_fmac_f32_e32 v91, v92, v89
	v_fma_f32 v88, -v88, v91, v90
	v_div_fmas_f32 v88, v88, v89, v91
	v_div_fixup_f32 v88, v88, v81, 1.0
	v_pk_mul_f32 v[78:79], v[78:79], v[88:89] op_sel_hi:[1,0]
	v_pk_mul_f32 v[76:77], v[76:77], v[88:89] op_sel_hi:[1,0]
	v_pk_mul_f32 v[74:75], v[74:75], v[88:89] op_sel_hi:[1,0]
	v_pk_mul_f32 v[72:73], v[72:73], v[88:89] op_sel_hi:[1,0]
	v_pk_mul_f32 v[70:71], v[70:71], v[88:89] op_sel_hi:[1,0]
	v_pk_mul_f32 v[68:69], v[68:69], v[88:89] op_sel_hi:[1,0]
	v_pk_mul_f32 v[90:91], v[66:67], v[88:89] op_sel_hi:[1,0]
	v_pk_mul_f32 v[88:89], v[64:65], v[88:89] op_sel_hi:[1,0]
	v_cvt_pk_bf16_f32 v64, v76, v77
	v_cvt_pk_bf16_f32 v65, v78, v79
	v_cvt_pk_bf16_f32 v66, v72, v73
	v_cvt_pk_bf16_f32 v67, v74, v75
	global_store_dwordx4 v[84:85], v[64:67], off
	s_nop 1
	v_cvt_pk_bf16_f32 v64, v68, v69
	v_cvt_pk_bf16_f32 v65, v70, v71
	v_cvt_pk_bf16_f32 v66, v88, v89
	v_cvt_pk_bf16_f32 v67, v90, v91
	global_store_dwordx4 v[86:87], v[64:67], off
	global_load_dword v244, v[82:83], off
	global_load_dword v245, v[82:83], off offset:64
	global_load_dword v246, v[82:83], off offset:128
	global_load_dword v247, v[82:83], off offset:192
	v_add_u32_e32 v68, s4, v145
	v_add_u32_e32 v64, s4, v156
	v_ashrrev_i32_e32 v65, 31, v64
	v_ashrrev_i32_e32 v69, 31, v68
	v_bitop3_b32 v70, s23, v199, v152 bitop3:0xc8
	v_lshlrev_b64 v[66:67], 12, v[64:65]
	v_lshlrev_b64 v[64:65], 12, v[68:69]
	v_or_b32_e32 v68, v66, v70
	v_or_b32_e32 v70, v64, v70
	v_mad_u64_u32 v[68:69], s[10:11], v68, s35, v[138:139]
	v_mad_u64_u32 v[70:71], s[10:11], v70, s35, v[138:139]
	v_mad_i32_i24 v69, v67, s35, v69
	v_mad_i32_i24 v71, v65, s35, v71
	v_lshl_add_u64 v[68:69], v[68:69], 0, v[140:141]
	v_lshl_add_u64 v[70:71], v[70:71], 0, v[142:143]
	s_waitcnt vmcnt(0)
	v_fmamk_f32 v72, v244, 0x3b000000, v197
	v_mul_f32_e32 v73, 0x4f800000, v72
	v_cmp_gt_f32_e32 vcc, s36, v72
	s_nop 1
	v_cndmask_b32_e32 v72, v72, v73, vcc
	v_sqrt_f32_e32 v73, v72
	s_nop 0
	v_add_u32_e32 v74, -1, v73
	v_add_u32_e32 v75, 1, v73
	v_fma_f32 v76, -v74, v73, v72
	v_fma_f32 v77, -v75, v73, v72
	v_cmp_ge_f32_e64 s[10:11], 0, v76
	s_nop 1
	v_cndmask_b32_e64 v73, v73, v74, s[10:11]
	v_cmp_lt_f32_e64 s[10:11], 0, v77
	s_nop 1
	v_cndmask_b32_e64 v73, v73, v75, s[10:11]
	v_mul_f32_e32 v74, 0x37800000, v73
	v_cndmask_b32_e32 v73, v73, v74, vcc
	v_cmp_class_f32_e32 vcc, v72, v198
	s_nop 1
	v_cndmask_b32_e32 v72, v73, v72, vcc
	v_div_scale_f32 v73, s[10:11], v72, v72, 1.0
	v_rcp_f32_e32 v74, v73
	v_div_scale_f32 v75, vcc, 1.0, v72, 1.0
	v_fma_f32 v76, -v73, v74, 1.0
	v_fmac_f32_e32 v74, v76, v74
	v_mul_f32_e32 v76, v75, v74
	v_fma_f32 v77, -v73, v76, v75
	v_fmac_f32_e32 v76, v77, v74
	v_fma_f32 v73, -v73, v76, v75
	v_div_fmas_f32 v73, v73, v74, v76
	v_div_fixup_f32 v72, v73, v72, 1.0
	v_pk_mul_f32 v[62:63], v[62:63], v[72:73] op_sel_hi:[1,0]
	v_pk_mul_f32 v[60:61], v[60:61], v[72:73] op_sel_hi:[1,0]
	v_pk_mul_f32 v[58:59], v[58:59], v[72:73] op_sel_hi:[1,0]
	v_pk_mul_f32 v[56:57], v[56:57], v[72:73] op_sel_hi:[1,0]
	v_pk_mul_f32 v[54:55], v[54:55], v[72:73] op_sel_hi:[1,0]
	v_pk_mul_f32 v[52:53], v[52:53], v[72:73] op_sel_hi:[1,0]
	v_pk_mul_f32 v[74:75], v[50:51], v[72:73] op_sel_hi:[1,0]
	v_pk_mul_f32 v[72:73], v[48:49], v[72:73] op_sel_hi:[1,0]
	v_cvt_pk_bf16_f32 v48, v60, v61
	v_cvt_pk_bf16_f32 v49, v62, v63
	v_cvt_pk_bf16_f32 v50, v56, v57
	v_cvt_pk_bf16_f32 v51, v58, v59
	global_store_dwordx4 v[68:69], v[48:51], off
	s_nop 1
	v_cvt_pk_bf16_f32 v48, v52, v53
	v_cvt_pk_bf16_f32 v49, v54, v55
	v_cvt_pk_bf16_f32 v50, v72, v73
	v_cvt_pk_bf16_f32 v51, v74, v75
	global_store_dwordx4 v[70:71], v[48:51], off
	s_nop 0
	s_nop 0
	v_fmamk_f32 v52, v245, 0x3b000000, v197
	v_mul_f32_e32 v53, 0x4f800000, v52
	v_cmp_gt_f32_e32 vcc, s36, v52
	v_bitop3_b32 v48, v80, s74, 16 bitop3:0xc8
	v_or_b32_e32 v49, v66, v48
	v_cndmask_b32_e32 v52, v52, v53, vcc
	v_sqrt_f32_e32 v53, v52
	v_or_b32_e32 v50, v64, v48
	v_mad_u64_u32 v[48:49], s[10:11], v49, s35, v[138:139]
	v_add_u32_e32 v54, -1, v53
	v_mad_u64_u32 v[50:51], s[10:11], v50, s35, v[138:139]
	v_add_u32_e32 v55, 1, v53
	v_fma_f32 v56, -v54, v53, v52
	v_fma_f32 v57, -v55, v53, v52
	v_cmp_ge_f32_e64 s[10:11], 0, v56
	v_mad_i32_i24 v49, v67, s35, v49
	v_mad_i32_i24 v51, v65, s35, v51
	v_cndmask_b32_e64 v53, v53, v54, s[10:11]
	v_cmp_lt_f32_e64 s[10:11], 0, v57
	v_lshl_add_u64 v[48:49], v[48:49], 0, v[140:141]
	v_lshl_add_u64 v[50:51], v[50:51], 0, v[142:143]
	v_cndmask_b32_e64 v53, v53, v55, s[10:11]
	v_mul_f32_e32 v54, 0x37800000, v53
	v_cndmask_b32_e32 v53, v53, v54, vcc
	v_cmp_class_f32_e32 vcc, v52, v198
	s_nop 1
	v_cndmask_b32_e32 v52, v53, v52, vcc
	v_div_scale_f32 v53, s[10:11], v52, v52, 1.0
	v_rcp_f32_e32 v54, v53
	v_div_scale_f32 v55, vcc, 1.0, v52, 1.0
	v_fma_f32 v56, -v53, v54, 1.0
	v_fmac_f32_e32 v54, v56, v54
	v_mul_f32_e32 v56, v55, v54
	v_fma_f32 v57, -v53, v56, v55
	v_fmac_f32_e32 v56, v57, v54
	v_fma_f32 v53, -v53, v56, v55
	v_div_fmas_f32 v53, v53, v54, v56
	v_div_fixup_f32 v52, v53, v52, 1.0
	v_pk_mul_f32 v[46:47], v[46:47], v[52:53] op_sel_hi:[1,0]
	v_pk_mul_f32 v[44:45], v[44:45], v[52:53] op_sel_hi:[1,0]
	v_pk_mul_f32 v[42:43], v[42:43], v[52:53] op_sel_hi:[1,0]
	v_pk_mul_f32 v[40:41], v[40:41], v[52:53] op_sel_hi:[1,0]
	v_pk_mul_f32 v[38:39], v[38:39], v[52:53] op_sel_hi:[1,0]
	v_pk_mul_f32 v[36:37], v[36:37], v[52:53] op_sel_hi:[1,0]
	v_pk_mul_f32 v[54:55], v[34:35], v[52:53] op_sel_hi:[1,0]
	v_pk_mul_f32 v[52:53], v[32:33], v[52:53] op_sel_hi:[1,0]
	v_cvt_pk_bf16_f32 v32, v44, v45
	v_cvt_pk_bf16_f32 v33, v46, v47
	v_cvt_pk_bf16_f32 v34, v40, v41
	v_cvt_pk_bf16_f32 v35, v42, v43
	global_store_dwordx4 v[48:49], v[32:35], off
	s_nop 1
	v_cvt_pk_bf16_f32 v32, v36, v37
	v_cvt_pk_bf16_f32 v33, v38, v39
	v_cvt_pk_bf16_f32 v34, v52, v53
	v_cvt_pk_bf16_f32 v35, v54, v55
	global_store_dwordx4 v[50:51], v[32:35], off
	s_nop 0
	s_nop 0
	v_fmamk_f32 v36, v246, 0x3b000000, v197
	v_mul_f32_e32 v37, 0x4f800000, v36
	v_cmp_gt_f32_e32 vcc, s36, v36
	v_bitop3_b32 v32, v80, s75, 32 bitop3:0xc8
	v_or_b32_e32 v33, v66, v32
	v_cndmask_b32_e32 v36, v36, v37, vcc
	v_sqrt_f32_e32 v37, v36
	v_or_b32_e32 v34, v64, v32
	v_mad_u64_u32 v[32:33], s[10:11], v33, s35, v[138:139]
	v_add_u32_e32 v38, -1, v37
	v_mad_u64_u32 v[34:35], s[10:11], v34, s35, v[138:139]
	v_add_u32_e32 v39, 1, v37
	v_fma_f32 v40, -v38, v37, v36
	v_fma_f32 v41, -v39, v37, v36
	v_cmp_ge_f32_e64 s[10:11], 0, v40
	v_mad_i32_i24 v33, v67, s35, v33
	v_mad_i32_i24 v35, v65, s35, v35
	v_cndmask_b32_e64 v37, v37, v38, s[10:11]
	v_cmp_lt_f32_e64 s[10:11], 0, v41
	v_lshl_add_u64 v[32:33], v[32:33], 0, v[140:141]
	v_lshl_add_u64 v[34:35], v[34:35], 0, v[142:143]
	v_cndmask_b32_e64 v37, v37, v39, s[10:11]
	v_mul_f32_e32 v38, 0x37800000, v37
	v_cndmask_b32_e32 v37, v37, v38, vcc
	v_cmp_class_f32_e32 vcc, v36, v198
	s_nop 1
	v_cndmask_b32_e32 v36, v37, v36, vcc
	v_div_scale_f32 v37, s[10:11], v36, v36, 1.0
	v_rcp_f32_e32 v38, v37
	v_div_scale_f32 v39, vcc, 1.0, v36, 1.0
	v_fma_f32 v40, -v37, v38, 1.0
	v_fmac_f32_e32 v38, v40, v38
	v_mul_f32_e32 v40, v39, v38
	v_fma_f32 v41, -v37, v40, v39
	v_fmac_f32_e32 v40, v41, v38
	v_fma_f32 v37, -v37, v40, v39
	v_div_fmas_f32 v37, v37, v38, v40
	v_div_fixup_f32 v36, v37, v36, 1.0
	v_pk_mul_f32 v[30:31], v[30:31], v[36:37] op_sel_hi:[1,0]
	v_pk_mul_f32 v[28:29], v[28:29], v[36:37] op_sel_hi:[1,0]
	v_pk_mul_f32 v[26:27], v[26:27], v[36:37] op_sel_hi:[1,0]
	v_pk_mul_f32 v[24:25], v[24:25], v[36:37] op_sel_hi:[1,0]
	v_pk_mul_f32 v[22:23], v[22:23], v[36:37] op_sel_hi:[1,0]
	v_pk_mul_f32 v[20:21], v[20:21], v[36:37] op_sel_hi:[1,0]
	v_pk_mul_f32 v[38:39], v[18:19], v[36:37] op_sel_hi:[1,0]
	v_pk_mul_f32 v[36:37], v[16:17], v[36:37] op_sel_hi:[1,0]
	v_cvt_pk_bf16_f32 v16, v28, v29
	v_cvt_pk_bf16_f32 v17, v30, v31
	v_cvt_pk_bf16_f32 v18, v24, v25
	v_cvt_pk_bf16_f32 v19, v26, v27
	global_store_dwordx4 v[32:33], v[16:19], off
	s_nop 1
	v_cvt_pk_bf16_f32 v16, v20, v21
	v_cvt_pk_bf16_f32 v17, v22, v23
	v_cvt_pk_bf16_f32 v18, v36, v37
	v_cvt_pk_bf16_f32 v19, v38, v39
	global_store_dwordx4 v[34:35], v[16:19], off
	s_nop 0
	s_nop 0
	v_fmamk_f32 v20, v247, 0x3b000000, v197
	v_mul_f32_e32 v21, 0x4f800000, v20
	v_cmp_gt_f32_e32 vcc, s36, v20
	v_bitop3_b32 v16, v80, s77, 48 bitop3:0xc8
	v_or_b32_e32 v17, v66, v16
	v_cndmask_b32_e32 v20, v20, v21, vcc
	v_sqrt_f32_e32 v21, v20
	v_or_b32_e32 v18, v64, v16
	v_mad_u64_u32 v[16:17], s[10:11], v17, s35, v[138:139]
	v_add_u32_e32 v22, -1, v21
	v_mad_u64_u32 v[18:19], s[10:11], v18, s35, v[138:139]
	v_add_u32_e32 v23, 1, v21
	v_fma_f32 v24, -v22, v21, v20
	v_fma_f32 v25, -v23, v21, v20
	v_cmp_ge_f32_e64 s[10:11], 0, v24
	v_mad_i32_i24 v17, v67, s35, v17
	v_mad_i32_i24 v19, v65, s35, v19
	v_cndmask_b32_e64 v21, v21, v22, s[10:11]
	v_cmp_lt_f32_e64 s[10:11], 0, v25
	v_lshl_add_u64 v[16:17], v[16:17], 0, v[140:141]
	v_lshl_add_u64 v[18:19], v[18:19], 0, v[142:143]
	v_cndmask_b32_e64 v21, v21, v23, s[10:11]
	v_mul_f32_e32 v22, 0x37800000, v21
	v_cndmask_b32_e32 v21, v21, v22, vcc
	v_cmp_class_f32_e32 vcc, v20, v198
	s_nop 1
	v_cndmask_b32_e32 v20, v21, v20, vcc
	v_div_scale_f32 v21, s[10:11], v20, v20, 1.0
	v_rcp_f32_e32 v22, v21
	v_div_scale_f32 v23, vcc, 1.0, v20, 1.0
	v_fma_f32 v24, -v21, v22, 1.0
	v_fmac_f32_e32 v22, v24, v22
	v_mul_f32_e32 v24, v23, v22
	v_fma_f32 v25, -v21, v24, v23
	v_fmac_f32_e32 v24, v25, v22
	v_fma_f32 v21, -v21, v24, v23
	v_div_fmas_f32 v21, v21, v22, v24
	v_div_fixup_f32 v20, v21, v20, 1.0
	s_andn2_b64 vcc, exec, s[8:9]
	v_pk_mul_f32 v[14:15], v[14:15], v[20:21] op_sel_hi:[1,0]
	v_pk_mul_f32 v[12:13], v[12:13], v[20:21] op_sel_hi:[1,0]
	v_pk_mul_f32 v[10:11], v[10:11], v[20:21] op_sel_hi:[1,0]
	v_pk_mul_f32 v[8:9], v[8:9], v[20:21] op_sel_hi:[1,0]
	v_pk_mul_f32 v[6:7], v[6:7], v[20:21] op_sel_hi:[1,0]
	v_pk_mul_f32 v[4:5], v[4:5], v[20:21] op_sel_hi:[1,0]
	v_pk_mul_f32 v[22:23], v[2:3], v[20:21] op_sel_hi:[1,0]
	v_pk_mul_f32 v[20:21], v[0:1], v[20:21] op_sel_hi:[1,0]
	v_cvt_pk_bf16_f32 v0, v12, v13
	v_cvt_pk_bf16_f32 v1, v14, v15
	v_cvt_pk_bf16_f32 v2, v8, v9
	v_cvt_pk_bf16_f32 v3, v10, v11
	s_mov_b64 s[8:9], -1
	global_store_dwordx4 v[16:17], v[0:3], off
	s_nop 1
	v_cvt_pk_bf16_f32 v0, v4, v5
	v_cvt_pk_bf16_f32 v1, v6, v7
	v_cvt_pk_bf16_f32 v2, v20, v21
	v_cvt_pk_bf16_f32 v3, v22, v23
	global_store_dwordx4 v[18:19], v[0:3], off
	s_cbranch_vccnz .LBB0_666
	s_andn2_b64 vcc, exec, s[12:13]
	s_cbranch_vccnz .LBB0_665
	s_barrier
	s_branch .LBB0_665
